# sample-row assemble de-serialised in NRM phase; final rmsnorm phase hand-written (hoisted gains, 4 rows in flight)
# speedup vs baseline: 1.0301x; 1.0301x over previous
; #define x_sample ((const float*)KPTR(1))
; __global__ void __launch_bounds__(NTHR, 2) fwd_kernel(Args a) {
;     ...
;               for (int m = MP + gw; m < MREAL; m += NGW) {
;                   if (rp_ == 0) sample_assemble(l == 0 ? x_sample + (size_t)(m - MP) * DM : XR + (size_t)m * DM, XSP, 8, m - MP, XR + (size_t)m * DM, lane);
;                   row_bf16_ss(XR + (size_t)m * DM, XN + (size_t)m * DM, SSB + (size_t)(2 * l + 1) * MPAD + m, lane); } }
.LBB0_714:
	s_or_b64 exec, exec, s[4:5]
	s_ashr_i32 s6, s6, 6
	v_readlane_b32 s0, v245, 26
	s_sub_i32 s4, s0, 0x2000
	s_lshr_b32 s4, s4, 3
	s_lshr_b32 s5, s96, 3
	s_mul_i32 s5, s5, s6
	s_add_i32 s4, s4, s5
	s_addk_i32 s4, 0x2000
	s_cmpk_gt_i32 s4, 0x207f
	s_cbranch_scc1 .LBB0_723
	s_load_dwordx2 s[8:9], s[2:3], 0x98
	v_and_b32_e32 v0, 63, v6
	v_lshlrev_b32_e32 v168, 4, v0
	s_mov_b64 s[22:23], 0xe700000
	v_and_b32_e32 v1, 64, v211
	s_waitcnt lgkmcnt(0)
	v_lshl_add_u64 v[2:3], s[8:9], 0, v[168:169]
	v_lshl_add_u64 v[32:33], v[2:3], 0, s[22:23]
	s_mov_b64 s[22:23], 0x216e4000
	v_lshl_add_u64 v[34:35], v[2:3], 0, s[22:23]
	v_add_u32_e32 v1, 64, v1
	v_xor_b32_e32 v2, 1, v211
	v_cmp_lt_i32_e32 vcc, v2, v1
	v_lshlrev_b32_e32 v168, 3, v0
	v_readlane_b32 s0, v244, 34
	v_cndmask_b32_e32 v2, v211, v2, vcc
	v_lshlrev_b32_e32 v38, 2, v2
	v_xor_b32_e32 v2, 2, v211
	v_cmp_lt_i32_e32 vcc, v2, v1
	s_mov_b64 s[22:23], 0xc600000
	v_readlane_b32 s1, v244, 35
	v_cndmask_b32_e32 v2, v211, v2, vcc
	v_lshlrev_b32_e32 v39, 2, v2
	v_xor_b32_e32 v2, 4, v211
	v_cmp_lt_i32_e32 vcc, v2, v1
	v_cmp_eq_u32_e64 s[40:41], 0, v0
	s_nop 0
	v_cndmask_b32_e32 v2, v211, v2, vcc
	v_lshlrev_b32_e32 v40, 2, v2
	v_xor_b32_e32 v2, 8, v211
	v_cmp_lt_i32_e32 vcc, v2, v1
	s_nop 1
	v_cndmask_b32_e32 v2, v211, v2, vcc
	v_lshlrev_b32_e32 v41, 2, v2
	v_xor_b32_e32 v2, 16, v211
	v_cmp_lt_i32_e32 vcc, v2, v1
	s_nop 1
	v_cndmask_b32_e32 v2, v211, v2, vcc
	v_lshlrev_b32_e32 v42, 2, v2
	v_xor_b32_e32 v2, 32, v211
	v_cmp_lt_i32_e32 vcc, v2, v1
	s_nop 1
	v_cndmask_b32_e32 v1, v211, v2, vcc
	v_lshl_add_u64 v[2:3], s[8:9], 0, v[168:169]
	v_lshl_add_u64 v[36:37], v[2:3], 0, s[22:23]
	s_lshl_b64 s[22:23], s[0:1], 2
	s_add_u32 s5, s8, s22
	s_addc_u32 s7, s9, s23
	s_add_u32 s10, s5, 0x221f0400
	v_readlane_b32 s0, v246, 4
	s_addc_u32 s34, s7, 0
	s_ashr_i32 s5, s4, 31
	s_add_i32 s24, s4, 0xffffe000
	v_readlane_b32 s0, v244, 30
	v_lshlrev_b32_e32 v43, 2, v1
	s_lshl_b64 s[22:23], s[4:5], 13
	v_readlane_b32 s1, v244, 31
	v_lshlrev_b32_e32 v168, 4, v0
	s_branch .LBB0_717

; __device__ __forceinline__ void sample_assemble(const float* base, const float* XSP, int nsp, int s, float* xr, int lane) {
;     const f32x4* br = (const f32x4*)base + lane; f32x4* o = (f32x4*)xr + lane;
; #pragma unroll
;     for (int j = 0; j < 8; ++j) { f32x4 v = br[64 * j];
;         for (int sp = 0; sp < nsp; ++sp) v += *((const f32x4*)(XSP + ((size_t)sp * NS + s) * DM) + lane + 64 * j);
;         o[64 * j] = v; }
; }
.LBB0_721:
	v_readfirstlane_b32 s98, v34
	v_readfirstlane_b32 s99, v35
	v_readfirstlane_b32 s100, v32
	v_readfirstlane_b32 s101, v33
	s_add_u32 s98, s98, s6
	s_addc_u32 s99, s99, s7
	s_add_u32 s100, s100, s30
	s_addc_u32 s101, s101, s31
	v_add_u32_e32 v0, 0x1000, v168
	global_load_dwordx4 v[82:85], v168, s[28:29]
	global_load_dwordx4 v[86:89], v168, s[98:99]
	s_add_u32 s6, s98, 0x100000
	s_addc_u32 s7, s99, 0
	global_load_dwordx4 v[90:93], v168, s[6:7]
	s_add_u32 s6, s98, 0x200000
	s_addc_u32 s7, s99, 0
	global_load_dwordx4 v[94:97], v168, s[6:7]
	s_add_u32 s6, s98, 0x300000
	s_addc_u32 s7, s99, 0
	global_load_dwordx4 v[98:101], v168, s[6:7]
	s_add_u32 s6, s98, 0x400000
	s_addc_u32 s7, s99, 0
	global_load_dwordx4 v[102:105], v168, s[6:7]
	s_add_u32 s6, s98, 0x500000
	s_addc_u32 s7, s99, 0
	global_load_dwordx4 v[128:131], v168, s[6:7]
	s_add_u32 s6, s98, 0x600000
	s_addc_u32 s7, s99, 0
	global_load_dwordx4 v[132:135], v168, s[6:7]
	s_add_u32 s6, s98, 0x700000
	s_addc_u32 s7, s99, 0
	global_load_dwordx4 v[136:139], v168, s[6:7]
	global_load_dwordx4 v[140:143], v168, s[28:29] offset:1024
	global_load_dwordx4 v[144:147], v168, s[98:99] offset:1024
	s_add_u32 s6, s98, 0x100000
	s_addc_u32 s7, s99, 0
	global_load_dwordx4 v[148:151], v168, s[6:7] offset:1024
	s_add_u32 s6, s98, 0x200000
	s_addc_u32 s7, s99, 0
	global_load_dwordx4 v[152:155], v168, s[6:7] offset:1024
	s_add_u32 s6, s98, 0x300000
	s_addc_u32 s7, s99, 0
	global_load_dwordx4 v[156:159], v168, s[6:7] offset:1024
	s_add_u32 s6, s98, 0x400000
	s_addc_u32 s7, s99, 0
	global_load_dwordx4 v[160:163], v168, s[6:7] offset:1024
	s_add_u32 s6, s98, 0x500000
	s_addc_u32 s7, s99, 0
	global_load_dwordx4 v[164:167], v168, s[6:7] offset:1024
	s_add_u32 s6, s98, 0x600000
	s_addc_u32 s7, s99, 0
	global_load_dwordx4 v[178:181], v168, s[6:7] offset:1024
	s_add_u32 s6, s98, 0x700000
	s_addc_u32 s7, s99, 0
	global_load_dwordx4 v[182:185], v168, s[6:7] offset:1024
	global_load_dwordx4 v[186:189], v168, s[28:29] offset:2048
	global_load_dwordx4 v[190:193], v168, s[98:99] offset:2048
	s_add_u32 s6, s98, 0x100000
	s_addc_u32 s7, s99, 0
	global_load_dwordx4 v[194:197], v168, s[6:7] offset:2048
	s_add_u32 s6, s98, 0x200000
	s_addc_u32 s7, s99, 0
	global_load_dwordx4 v[198:201], v168, s[6:7] offset:2048
	s_add_u32 s6, s98, 0x300000
	s_addc_u32 s7, s99, 0
	global_load_dwordx4 v[202:205], v168, s[6:7] offset:2048
	s_add_u32 s6, s98, 0x400000
	s_addc_u32 s7, s99, 0
	global_load_dwordx4 v[206:209], v168, s[6:7] offset:2048
	s_add_u32 s6, s98, 0x500000
	s_addc_u32 s7, s99, 0
	global_load_dwordx4 v[226:229], v168, s[6:7] offset:2048
	s_add_u32 s6, s98, 0x600000
	s_addc_u32 s7, s99, 0
	global_load_dwordx4 v[230:233], v168, s[6:7] offset:2048
	s_add_u32 s6, s98, 0x700000
	s_addc_u32 s7, s99, 0
	global_load_dwordx4 v[234:237], v168, s[6:7] offset:2048
	s_waitcnt vmcnt(18)
	v_pk_add_f32 v[2:3], v[82:83], v[86:87]
	v_pk_add_f32 v[4:5], v[84:85], v[88:89]
	v_pk_add_f32 v[2:3], v[2:3], v[90:91]
	v_pk_add_f32 v[4:5], v[4:5], v[92:93]
	v_pk_add_f32 v[2:3], v[2:3], v[94:95]
	v_pk_add_f32 v[4:5], v[4:5], v[96:97]
	v_pk_add_f32 v[2:3], v[2:3], v[98:99]
	v_pk_add_f32 v[4:5], v[4:5], v[100:101]
	v_pk_add_f32 v[2:3], v[2:3], v[102:103]
	v_pk_add_f32 v[4:5], v[4:5], v[104:105]
	v_pk_add_f32 v[2:3], v[2:3], v[128:129]
	v_pk_add_f32 v[4:5], v[4:5], v[130:131]
	v_pk_add_f32 v[2:3], v[2:3], v[132:133]
	v_pk_add_f32 v[4:5], v[4:5], v[134:135]
	v_pk_add_f32 v[2:3], v[2:3], v[136:137]
	v_pk_add_f32 v[4:5], v[4:5], v[138:139]
	global_store_dwordx4 v168, v[2:5], s[100:101]
	global_load_dwordx4 v[82:85], v168, s[28:29] offset:3072
	global_load_dwordx4 v[86:89], v168, s[98:99] offset:3072
	s_add_u32 s6, s98, 0x100000
	s_addc_u32 s7, s99, 0
	global_load_dwordx4 v[90:93], v168, s[6:7] offset:3072
	s_add_u32 s6, s98, 0x200000
	s_addc_u32 s7, s99, 0
	global_load_dwordx4 v[94:97], v168, s[6:7] offset:3072
	s_add_u32 s6, s98, 0x300000
	s_addc_u32 s7, s99, 0
	global_load_dwordx4 v[98:101], v168, s[6:7] offset:3072
	s_add_u32 s6, s98, 0x400000
	s_addc_u32 s7, s99, 0
	global_load_dwordx4 v[102:105], v168, s[6:7] offset:3072
	s_add_u32 s6, s98, 0x500000
	s_addc_u32 s7, s99, 0
	global_load_dwordx4 v[128:131], v168, s[6:7] offset:3072
	s_add_u32 s6, s98, 0x600000
	s_addc_u32 s7, s99, 0
	global_load_dwordx4 v[132:135], v168, s[6:7] offset:3072
	s_add_u32 s6, s98, 0x700000
	s_addc_u32 s7, s99, 0
	global_load_dwordx4 v[136:139], v168, s[6:7] offset:3072
	s_waitcnt vmcnt(19)
	v_pk_add_f32 v[6:7], v[140:141], v[144:145]
	v_pk_add_f32 v[8:9], v[142:143], v[146:147]
	v_pk_add_f32 v[6:7], v[6:7], v[148:149]
	v_pk_add_f32 v[8:9], v[8:9], v[150:151]
	v_pk_add_f32 v[6:7], v[6:7], v[152:153]
	v_pk_add_f32 v[8:9], v[8:9], v[154:155]
	v_pk_add_f32 v[6:7], v[6:7], v[156:157]
	v_pk_add_f32 v[8:9], v[8:9], v[158:159]
	v_pk_add_f32 v[6:7], v[6:7], v[160:161]
	v_pk_add_f32 v[8:9], v[8:9], v[162:163]
	v_pk_add_f32 v[6:7], v[6:7], v[164:165]
	v_pk_add_f32 v[8:9], v[8:9], v[166:167]
	v_pk_add_f32 v[6:7], v[6:7], v[178:179]
	v_pk_add_f32 v[8:9], v[8:9], v[180:181]
	v_pk_add_f32 v[6:7], v[6:7], v[182:183]
	v_pk_add_f32 v[8:9], v[8:9], v[184:185]
	global_store_dwordx4 v168, v[6:9], s[100:101] offset:1024
	global_load_dwordx4 v[140:143], v0, s[28:29]
	global_load_dwordx4 v[144:147], v0, s[98:99]
	s_add_u32 s6, s98, 0x100000
	s_addc_u32 s7, s99, 0
	global_load_dwordx4 v[148:151], v0, s[6:7]
	s_add_u32 s6, s98, 0x200000
	s_addc_u32 s7, s99, 0
	global_load_dwordx4 v[152:155], v0, s[6:7]
	s_add_u32 s6, s98, 0x300000
	s_addc_u32 s7, s99, 0
	global_load_dwordx4 v[156:159], v0, s[6:7]
	s_add_u32 s6, s98, 0x400000
	s_addc_u32 s7, s99, 0
	global_load_dwordx4 v[160:163], v0, s[6:7]
	s_add_u32 s6, s98, 0x500000
	s_addc_u32 s7, s99, 0
	global_load_dwordx4 v[164:167], v0, s[6:7]
	s_add_u32 s6, s98, 0x600000
	s_addc_u32 s7, s99, 0
	global_load_dwordx4 v[178:181], v0, s[6:7]
	s_add_u32 s6, s98, 0x700000
	s_addc_u32 s7, s99, 0
	global_load_dwordx4 v[182:185], v0, s[6:7]
	s_waitcnt vmcnt(20)
; __device__ __forceinline__ void sample_assemble(const float* base, const float* XSP, int nsp, int s, float* xr, int lane) {
;     const f32x4* br = (const f32x4*)base + lane; f32x4* o = (f32x4*)xr + lane;
; #pragma unroll
;     for (int j = 0; j < 8; ++j) { f32x4 v = br[64 * j];
;         for (int sp = 0; sp < nsp; ++sp) v += *((const f32x4*)(XSP + ((size_t)sp * NS + s) * DM) + lane + 64 * j);
;         o[64 * j] = v; }
; }
	v_pk_add_f32 v[10:11], v[186:187], v[190:191]
	v_pk_add_f32 v[12:13], v[188:189], v[192:193]
	v_pk_add_f32 v[10:11], v[10:11], v[194:195]
	v_pk_add_f32 v[12:13], v[12:13], v[196:197]
	v_pk_add_f32 v[10:11], v[10:11], v[198:199]
	v_pk_add_f32 v[12:13], v[12:13], v[200:201]
	v_pk_add_f32 v[10:11], v[10:11], v[202:203]
	v_pk_add_f32 v[12:13], v[12:13], v[204:205]
	v_pk_add_f32 v[10:11], v[10:11], v[206:207]
	v_pk_add_f32 v[12:13], v[12:13], v[208:209]
	v_pk_add_f32 v[10:11], v[10:11], v[226:227]
	v_pk_add_f32 v[12:13], v[12:13], v[228:229]
	v_pk_add_f32 v[10:11], v[10:11], v[230:231]
	v_pk_add_f32 v[12:13], v[12:13], v[232:233]
	v_pk_add_f32 v[10:11], v[10:11], v[234:235]
	v_pk_add_f32 v[12:13], v[12:13], v[236:237]
	global_store_dwordx4 v168, v[10:13], s[100:101] offset:2048
	global_load_dwordx4 v[186:189], v0, s[28:29] offset:1024
	global_load_dwordx4 v[190:193], v0, s[98:99] offset:1024
	s_add_u32 s6, s98, 0x100000
	s_addc_u32 s7, s99, 0
	global_load_dwordx4 v[194:197], v0, s[6:7] offset:1024
	s_add_u32 s6, s98, 0x200000
	s_addc_u32 s7, s99, 0
	global_load_dwordx4 v[198:201], v0, s[6:7] offset:1024
	s_add_u32 s6, s98, 0x300000
	s_addc_u32 s7, s99, 0
	global_load_dwordx4 v[202:205], v0, s[6:7] offset:1024
	s_add_u32 s6, s98, 0x400000
	s_addc_u32 s7, s99, 0
	global_load_dwordx4 v[206:209], v0, s[6:7] offset:1024
	s_add_u32 s6, s98, 0x500000
	s_addc_u32 s7, s99, 0
	global_load_dwordx4 v[226:229], v0, s[6:7] offset:1024
	s_add_u32 s6, s98, 0x600000
	s_addc_u32 s7, s99, 0
	global_load_dwordx4 v[230:233], v0, s[6:7] offset:1024
	s_add_u32 s6, s98, 0x700000
	s_addc_u32 s7, s99, 0
	global_load_dwordx4 v[234:237], v0, s[6:7] offset:1024
	s_waitcnt vmcnt(20)
	v_pk_add_f32 v[14:15], v[82:83], v[86:87]
	v_pk_add_f32 v[16:17], v[84:85], v[88:89]
	v_pk_add_f32 v[14:15], v[14:15], v[90:91]
	v_pk_add_f32 v[16:17], v[16:17], v[92:93]
	v_pk_add_f32 v[14:15], v[14:15], v[94:95]
	v_pk_add_f32 v[16:17], v[16:17], v[96:97]
	v_pk_add_f32 v[14:15], v[14:15], v[98:99]
	v_pk_add_f32 v[16:17], v[16:17], v[100:101]
	v_pk_add_f32 v[14:15], v[14:15], v[102:103]
	v_pk_add_f32 v[16:17], v[16:17], v[104:105]
	v_pk_add_f32 v[14:15], v[14:15], v[128:129]
	v_pk_add_f32 v[16:17], v[16:17], v[130:131]
	v_pk_add_f32 v[14:15], v[14:15], v[132:133]
	v_pk_add_f32 v[16:17], v[16:17], v[134:135]
	v_pk_add_f32 v[14:15], v[14:15], v[136:137]
	v_pk_add_f32 v[16:17], v[16:17], v[138:139]
	global_store_dwordx4 v168, v[14:17], s[100:101] offset:3072
	global_load_dwordx4 v[82:85], v0, s[28:29] offset:2048
	global_load_dwordx4 v[86:89], v0, s[98:99] offset:2048
	s_add_u32 s6, s98, 0x100000
	s_addc_u32 s7, s99, 0
	global_load_dwordx4 v[90:93], v0, s[6:7] offset:2048
	s_add_u32 s6, s98, 0x200000
	s_addc_u32 s7, s99, 0
	global_load_dwordx4 v[94:97], v0, s[6:7] offset:2048
	s_add_u32 s6, s98, 0x300000
	s_addc_u32 s7, s99, 0
	global_load_dwordx4 v[98:101], v0, s[6:7] offset:2048
	s_add_u32 s6, s98, 0x400000
	s_addc_u32 s7, s99, 0
	global_load_dwordx4 v[102:105], v0, s[6:7] offset:2048
	s_add_u32 s6, s98, 0x500000
	s_addc_u32 s7, s99, 0
	global_load_dwordx4 v[128:131], v0, s[6:7] offset:2048
	s_add_u32 s6, s98, 0x600000
	s_addc_u32 s7, s99, 0
	global_load_dwordx4 v[132:135], v0, s[6:7] offset:2048
	s_add_u32 s6, s98, 0x700000
	s_addc_u32 s7, s99, 0
	global_load_dwordx4 v[136:139], v0, s[6:7] offset:2048
	s_waitcnt vmcnt(20)
	v_pk_add_f32 v[18:19], v[140:141], v[144:145]
	v_pk_add_f32 v[20:21], v[142:143], v[146:147]
	v_pk_add_f32 v[18:19], v[18:19], v[148:149]
	v_pk_add_f32 v[20:21], v[20:21], v[150:151]
	v_pk_add_f32 v[18:19], v[18:19], v[152:153]
	v_pk_add_f32 v[20:21], v[20:21], v[154:155]
	v_pk_add_f32 v[18:19], v[18:19], v[156:157]
	v_pk_add_f32 v[20:21], v[20:21], v[158:159]
	v_pk_add_f32 v[18:19], v[18:19], v[160:161]
	v_pk_add_f32 v[20:21], v[20:21], v[162:163]
	v_pk_add_f32 v[18:19], v[18:19], v[164:165]
	v_pk_add_f32 v[20:21], v[20:21], v[166:167]
	v_pk_add_f32 v[18:19], v[18:19], v[178:179]
	v_pk_add_f32 v[20:21], v[20:21], v[180:181]
	v_pk_add_f32 v[18:19], v[18:19], v[182:183]
	v_pk_add_f32 v[20:21], v[20:21], v[184:185]
	global_store_dwordx4 v0, v[18:21], s[100:101]
	global_load_dwordx4 v[140:143], v0, s[28:29] offset:3072
	global_load_dwordx4 v[144:147], v0, s[98:99] offset:3072
	s_add_u32 s6, s98, 0x100000
	s_addc_u32 s7, s99, 0
	global_load_dwordx4 v[148:151], v0, s[6:7] offset:3072
	s_add_u32 s6, s98, 0x200000
	s_addc_u32 s7, s99, 0
	global_load_dwordx4 v[152:155], v0, s[6:7] offset:3072
	s_add_u32 s6, s98, 0x300000
	s_addc_u32 s7, s99, 0
	global_load_dwordx4 v[156:159], v0, s[6:7] offset:3072
	s_add_u32 s6, s98, 0x400000
	s_addc_u32 s7, s99, 0
	global_load_dwordx4 v[160:163], v0, s[6:7] offset:3072
	s_add_u32 s6, s98, 0x500000
	s_addc_u32 s7, s99, 0
	global_load_dwordx4 v[164:167], v0, s[6:7] offset:3072
	s_add_u32 s6, s98, 0x600000
	s_addc_u32 s7, s99, 0
	global_load_dwordx4 v[178:181], v0, s[6:7] offset:3072
	s_add_u32 s6, s98, 0x700000
	s_addc_u32 s7, s99, 0
	global_load_dwordx4 v[182:185], v0, s[6:7] offset:3072
	s_waitcnt vmcnt(20)
; __device__ __forceinline__ unsigned cvt_pk_bf16(float lo, float hi) { unsigned r; asm volatile("v_cvt_pk_bf16_f32 %0, %1, %2" : "=v"(r) : "v"(lo), "v"(hi)); return r; }
; __device__ __forceinline__ void row_bf16_ss(const float* xrow, bf16_t* orow, float* ss, int lane) {
;     const f32x4* xr = (const f32x4*)xrow + lane; f32x4 v[8]; float s = 0.f;
; #pragma unroll
;     for (int j = 0; j < 8; ++j) { v[j] = xr[64 * j]; s += (v[j].x * v[j].x + v[j].y * v[j].y) + (v[j].z * v[j].z + v[j].w * v[j].w); }
;     s = wave_sum(s); u32x2* o8 = (u32x2*)orow + lane;
; #pragma unroll
;     for (int j = 0; j < 8; ++j) { u32x2 w; w.x = cvt_pk_bf16(v[j].x, v[j].y); w.y = cvt_pk_bf16(v[j].z, v[j].w); o8[64 * j] = w; }
;     if (lane == 0) *ss = s;
; }
; __device__ __forceinline__ void sample_assemble(const float* base, const float* XSP, int nsp, int s, float* xr, int lane) {
;     const f32x4* br = (const f32x4*)base + lane; f32x4* o = (f32x4*)xr + lane;
; #pragma unroll
;     for (int j = 0; j < 8; ++j) { f32x4 v = br[64 * j];
;         for (int sp = 0; sp < nsp; ++sp) v += *((const f32x4*)(XSP + ((size_t)sp * NS + s) * DM) + lane + 64 * j);
;         o[64 * j] = v; }
; }
	v_pk_add_f32 v[22:23], v[186:187], v[190:191]
	v_pk_add_f32 v[24:25], v[188:189], v[192:193]
	v_pk_add_f32 v[22:23], v[22:23], v[194:195]
	v_pk_add_f32 v[24:25], v[24:25], v[196:197]
	v_pk_add_f32 v[22:23], v[22:23], v[198:199]
	v_pk_add_f32 v[24:25], v[24:25], v[200:201]
	v_pk_add_f32 v[22:23], v[22:23], v[202:203]
	v_pk_add_f32 v[24:25], v[24:25], v[204:205]
	v_pk_add_f32 v[22:23], v[22:23], v[206:207]
	v_pk_add_f32 v[24:25], v[24:25], v[208:209]
	v_pk_add_f32 v[22:23], v[22:23], v[226:227]
	v_pk_add_f32 v[24:25], v[24:25], v[228:229]
	v_pk_add_f32 v[22:23], v[22:23], v[230:231]
	v_pk_add_f32 v[24:25], v[24:25], v[232:233]
	v_pk_add_f32 v[22:23], v[22:23], v[234:235]
	v_pk_add_f32 v[24:25], v[24:25], v[236:237]
	global_store_dwordx4 v0, v[22:25], s[100:101] offset:1024
	s_waitcnt vmcnt(11)
	v_pk_add_f32 v[26:27], v[82:83], v[86:87]
	v_pk_add_f32 v[28:29], v[84:85], v[88:89]
	v_pk_add_f32 v[26:27], v[26:27], v[90:91]
	v_pk_add_f32 v[28:29], v[28:29], v[92:93]
	v_pk_add_f32 v[26:27], v[26:27], v[94:95]
	v_pk_add_f32 v[28:29], v[28:29], v[96:97]
	v_pk_add_f32 v[26:27], v[26:27], v[98:99]
	v_pk_add_f32 v[28:29], v[28:29], v[100:101]
	v_pk_add_f32 v[26:27], v[26:27], v[102:103]
	v_pk_add_f32 v[28:29], v[28:29], v[104:105]
	v_pk_add_f32 v[26:27], v[26:27], v[128:129]
	v_pk_add_f32 v[28:29], v[28:29], v[130:131]
	v_pk_add_f32 v[26:27], v[26:27], v[132:133]
	v_pk_add_f32 v[28:29], v[28:29], v[134:135]
	v_pk_add_f32 v[26:27], v[26:27], v[136:137]
	v_pk_add_f32 v[28:29], v[28:29], v[138:139]
	global_store_dwordx4 v0, v[26:29], s[100:101] offset:2048
	s_waitcnt vmcnt(2)
	v_pk_add_f32 v[78:79], v[140:141], v[144:145]
	v_pk_add_f32 v[80:81], v[142:143], v[146:147]
	v_pk_add_f32 v[78:79], v[78:79], v[148:149]
	v_pk_add_f32 v[80:81], v[80:81], v[150:151]
	v_pk_add_f32 v[78:79], v[78:79], v[152:153]
	v_pk_add_f32 v[80:81], v[80:81], v[154:155]
	v_pk_add_f32 v[78:79], v[78:79], v[156:157]
	v_pk_add_f32 v[80:81], v[80:81], v[158:159]
	v_pk_add_f32 v[78:79], v[78:79], v[160:161]
	v_pk_add_f32 v[80:81], v[80:81], v[162:163]
	v_pk_add_f32 v[78:79], v[78:79], v[164:165]
	v_pk_add_f32 v[80:81], v[80:81], v[166:167]
	v_pk_add_f32 v[78:79], v[78:79], v[178:179]
	v_pk_add_f32 v[80:81], v[80:81], v[180:181]
	v_pk_add_f32 v[78:79], v[78:79], v[182:183]
	v_pk_add_f32 v[80:81], v[80:81], v[184:185]
	global_store_dwordx4 v0, v[78:81], s[100:101] offset:3072
	v_mul_f32_e32 v44, v3, v3
	v_mul_f32_e32 v30, v5, v5
	v_fmac_f32_e32 v44, v2, v2
	v_fmac_f32_e32 v30, v4, v4
	v_add_f32_e32 v44, v44, v30
	v_mul_f32_e32 v1, v7, v7
	v_mul_f32_e32 v30, v9, v9
	v_fmac_f32_e32 v1, v6, v6
	v_fmac_f32_e32 v30, v8, v8
	v_add_f32_e32 v1, v1, v30
	v_add_f32_e32 v44, v44, v1
	v_mul_f32_e32 v1, v11, v11
	v_mul_f32_e32 v30, v13, v13
	v_fmac_f32_e32 v1, v10, v10
	v_fmac_f32_e32 v30, v12, v12
	v_add_f32_e32 v1, v1, v30
	v_add_f32_e32 v44, v44, v1
	v_mul_f32_e32 v1, v15, v15
	v_mul_f32_e32 v30, v17, v17
	v_fmac_f32_e32 v1, v14, v14
	v_fmac_f32_e32 v30, v16, v16
	v_add_f32_e32 v1, v1, v30
	v_add_f32_e32 v44, v44, v1
	v_mul_f32_e32 v1, v19, v19
	v_mul_f32_e32 v30, v21, v21
	v_fmac_f32_e32 v1, v18, v18
	v_fmac_f32_e32 v30, v20, v20
	v_add_f32_e32 v1, v1, v30
	v_add_f32_e32 v44, v44, v1
	v_mul_f32_e32 v1, v23, v23
	v_mul_f32_e32 v30, v25, v25
	v_fmac_f32_e32 v1, v22, v22
	v_fmac_f32_e32 v30, v24, v24
	v_add_f32_e32 v1, v1, v30
	v_add_f32_e32 v44, v44, v1
	v_mul_f32_e32 v1, v27, v27
	v_mul_f32_e32 v30, v29, v29
	v_fmac_f32_e32 v1, v26, v26
	v_fmac_f32_e32 v30, v28, v28
	v_add_f32_e32 v1, v1, v30
	v_add_f32_e32 v44, v44, v1
	v_mul_f32_e32 v1, v79, v79
	v_mul_f32_e32 v30, v81, v81
	v_fmac_f32_e32 v1, v78, v78
	v_fmac_f32_e32 v30, v80, v80
	v_add_f32_e32 v1, v1, v30
	v_add_f32_e32 v44, v44, v1
	v_lshrrev_b32_e32 v47, 1, v168
	v_readfirstlane_b32 s6, v36
	v_readfirstlane_b32 s7, v37
	s_lshl_b64 s[98:99], s[26:27], 12
	s_add_u32 s6, s6, s98
	s_addc_u32 s7, s7, s99
	v_cvt_pk_bf16_f32 v106, v2, v3
	v_cvt_pk_bf16_f32 v107, v4, v5
	global_store_dwordx2 v47, v[106:107], s[6:7]
	v_cvt_pk_bf16_f32 v238, v6, v7
	v_cvt_pk_bf16_f32 v239, v8, v9
	global_store_dwordx2 v47, v[238:239], s[6:7] offset:512
	v_cvt_pk_bf16_f32 v240, v10, v11
	v_cvt_pk_bf16_f32 v241, v12, v13
	global_store_dwordx2 v47, v[240:241], s[6:7] offset:1024
	v_cvt_pk_bf16_f32 v242, v14, v15
	v_cvt_pk_bf16_f32 v243, v16, v17
	global_store_dwordx2 v47, v[242:243], s[6:7] offset:1536
	v_cvt_pk_bf16_f32 v248, v18, v19
	v_cvt_pk_bf16_f32 v249, v20, v21
	global_store_dwordx2 v47, v[248:249], s[6:7] offset:2048
	v_cvt_pk_bf16_f32 v250, v22, v23
	v_cvt_pk_bf16_f32 v251, v24, v25
	global_store_dwordx2 v47, v[250:251], s[6:7] offset:2560
	v_cvt_pk_bf16_f32 v252, v26, v27
	v_cvt_pk_bf16_f32 v253, v28, v29
	global_store_dwordx2 v47, v[252:253], s[6:7] offset:3072
	v_cvt_pk_bf16_f32 v254, v78, v79
	v_cvt_pk_bf16_f32 v255, v80, v81
	global_store_dwordx2 v47, v[254:255], s[6:7] offset:3584
	ds_bpermute_b32 v45, v38, v44
	s_waitcnt lgkmcnt(0)
	v_add_f32_e32 v44, v44, v45
	ds_bpermute_b32 v45, v39, v44
	s_waitcnt lgkmcnt(0)
	v_add_f32_e32 v44, v44, v45
	ds_bpermute_b32 v45, v40, v44
	s_waitcnt lgkmcnt(0)
	v_add_f32_e32 v44, v44, v45
	ds_bpermute_b32 v45, v41, v44
	s_waitcnt lgkmcnt(0)
	v_add_f32_e32 v44, v44, v45
	ds_bpermute_b32 v45, v42, v44
	s_waitcnt lgkmcnt(0)
	v_add_f32_e32 v44, v44, v45
	ds_bpermute_b32 v45, v43, v44
	s_and_saveexec_b64 s[6:7], s[40:41]
	s_cbranch_execz .LBB0_716
	s_lshl_b64 s[8:9], s[26:27], 2
	s_add_u32 s8, s10, s8
	s_waitcnt lgkmcnt(0)
	v_add_f32_e32 v0, v44, v45
	s_addc_u32 s9, s34, s9
	global_store_dword v169, v0, s[8:9]
	s_branch .LBB0_716

; __device__ __forceinline__ float bf_lo(unsigned w) { return __uint_as_float(w << 16); }
; __device__ __forceinline__ float bf_hi(unsigned w) { return __uint_as_float(w & 0xffff0000u); }
; __global__ void __launch_bounds__(NTHR, 2) fwd_kernel(Args a) {
;     ...
;     PHASE_IDS
;     if (bid == 0 && tid == 0) __hip_atomic_store((unsigned*)(ws + WS_BAR) + 4000, 0u, __ATOMIC_RELAXED, __HIP_MEMORY_SCOPE_AGENT);
;     for (int m = gw; m < MREAL; m += NGW) {
;         if (m >= MP) { sample_assemble(XR + (size_t)m * DM, XSP, 11, m - MP, XR + (size_t)m * DM, lane); rms_row_f32(XR + (size_t)m * DM, final_norm_g, out + O_YS + (size_t)(m - MP) * DM, lane); }
;         else { const u32x2* xr = (const u32x2*)(XN + (size_t)m * DM) + lane; f32x4 v[8]; float sq = 0.f;
; #pragma unroll
;             for (int j = 0; j < 8; ++j) { const u32x2 w = xr[64 * j]; v[j] = (f32x4){bf_lo(w.x), bf_hi(w.x), bf_lo(w.y), bf_hi(w.y)}; sq += (v[j].x * v[j].x + v[j].y * v[j].y) + (v[j].z * v[j].z + v[j].w * v[j].w); }
;             const float rstd = rsqrtf(wave_sum(sq) * (1.f / DM) + EPS); const f32x4* gr = (const f32x4*)final_norm_g + lane; f32x4* o = (f32x4*)(out + O_YP + (size_t)m * DM) + lane;
; #pragma unroll
;             for (int j = 0; j < 8; ++j) o[64 * j] = v[j] * rstd * gr[64 * j]; } }
.LBB0_1074:
	s_or_b64 exec, exec, s[0:1]
	v_readfirstlane_b32 s0, v210
	v_readlane_b32 s1, v246, 4
	s_load_dwordx4 s[4:7], s[90:91], 0x88
	s_load_dwordx2 s[8:9], s[90:91], 0x98
	s_lshr_b32 s0, s0, 6
	s_lshr_b32 s13, s1, 3
	s_add_i32 s3, s1, s0
	s_lshr_b32 s14, s96, 3
	s_mul_i32 s14, s14, s0
	s_add_i32 s14, s14, s13
	v_lshlrev_b32_e32 v0, 4, v211
	v_lshlrev_b32_e32 v1, 3, v211
	v_add_u32_e32 v2, 0x1000, v0
	v_xor_b32_e32 v3, 1, v211
	v_xor_b32_e32 v4, 2, v211
	v_xor_b32_e32 v5, 4, v211
	v_xor_b32_e32 v6, 8, v211
	v_xor_b32_e32 v7, 16, v211
	v_xor_b32_e32 v8, 32, v211
	v_lshlrev_b32_e32 v3, 2, v3
	v_lshlrev_b32_e32 v4, 2, v4
	v_lshlrev_b32_e32 v5, 2, v5
	v_lshlrev_b32_e32 v6, 2, v6
	v_lshlrev_b32_e32 v7, 2, v7
	v_lshlrev_b32_e32 v8, 2, v8
	v_mov_b32_e32 v9, 0x358637bd
	s_mov_b32 s12, 0x800000
	s_waitcnt lgkmcnt(0)
	global_load_dwordx4 v[16:19], v0, s[4:5]
	global_load_dwordx4 v[20:23], v0, s[4:5] offset:1024
	global_load_dwordx4 v[24:27], v0, s[4:5] offset:2048
	global_load_dwordx4 v[28:31], v0, s[4:5] offset:3072
	global_load_dwordx4 v[32:35], v2, s[4:5]
	global_load_dwordx4 v[36:39], v2, s[4:5] offset:1024
	global_load_dwordx4 v[40:43], v2, s[4:5] offset:2048
	global_load_dwordx4 v[44:47], v2, s[4:5] offset:3072
	s_add_u32 s10, s8, 0xc600000
	s_addc_u32 s11, s9, 0
	s_lshl_b32 s15, s96, 2
	s_cmp_ge_u32 s3, 0x2000
	s_cbranch_scc1 .Lfin_prompt_done
.Lfin_prompt_loop:
	s_mov_b32 s20, s3
	s_add_i32 s21, s20, s96
	s_add_i32 s22, s21, s96
	s_add_i32 s23, s22, s96
	s_cmp_lt_u32 s21, 0x2000
	s_cselect_b32 s25, 1, 0
	s_cselect_b32 s21, s21, s3
	s_cmp_lt_u32 s22, 0x2000
	s_cselect_b32 s26, 1, 0
	s_cselect_b32 s22, s22, s3
	s_cmp_lt_u32 s23, 0x2000
	s_cselect_b32 s27, 1, 0
	s_cselect_b32 s23, s23, s3
	s_lshl_b32 s16, s20, 12
	s_add_u32 s16, s10, s16
	s_addc_u32 s17, s11, 0
	global_load_dwordx2 v[48:49], v1, s[16:17]
	global_load_dwordx2 v[50:51], v1, s[16:17] offset:512
	global_load_dwordx2 v[52:53], v1, s[16:17] offset:1024
	global_load_dwordx2 v[54:55], v1, s[16:17] offset:1536
	global_load_dwordx2 v[56:57], v1, s[16:17] offset:2048
	global_load_dwordx2 v[58:59], v1, s[16:17] offset:2560
	global_load_dwordx2 v[60:61], v1, s[16:17] offset:3072
	global_load_dwordx2 v[62:63], v1, s[16:17] offset:3584
	s_lshl_b32 s16, s21, 12
	s_add_u32 s16, s10, s16
	s_addc_u32 s17, s11, 0
	global_load_dwordx2 v[64:65], v1, s[16:17]
	global_load_dwordx2 v[66:67], v1, s[16:17] offset:512
	global_load_dwordx2 v[68:69], v1, s[16:17] offset:1024
	global_load_dwordx2 v[70:71], v1, s[16:17] offset:1536
	global_load_dwordx2 v[72:73], v1, s[16:17] offset:2048
	global_load_dwordx2 v[74:75], v1, s[16:17] offset:2560
	global_load_dwordx2 v[76:77], v1, s[16:17] offset:3072
	global_load_dwordx2 v[78:79], v1, s[16:17] offset:3584
	s_lshl_b32 s16, s22, 12
	s_add_u32 s16, s10, s16
	s_addc_u32 s17, s11, 0
	global_load_dwordx2 v[80:81], v1, s[16:17]
	global_load_dwordx2 v[82:83], v1, s[16:17] offset:512
	global_load_dwordx2 v[84:85], v1, s[16:17] offset:1024
	global_load_dwordx2 v[86:87], v1, s[16:17] offset:1536
	global_load_dwordx2 v[88:89], v1, s[16:17] offset:2048
	global_load_dwordx2 v[90:91], v1, s[16:17] offset:2560
	global_load_dwordx2 v[92:93], v1, s[16:17] offset:3072
	global_load_dwordx2 v[94:95], v1, s[16:17] offset:3584
	s_lshl_b32 s16, s23, 12
	s_add_u32 s16, s10, s16
	s_addc_u32 s17, s11, 0
	global_load_dwordx2 v[96:97], v1, s[16:17]
	global_load_dwordx2 v[98:99], v1, s[16:17] offset:512
	global_load_dwordx2 v[100:101], v1, s[16:17] offset:1024
	global_load_dwordx2 v[102:103], v1, s[16:17] offset:1536
	global_load_dwordx2 v[104:105], v1, s[16:17] offset:2048
	global_load_dwordx2 v[106:107], v1, s[16:17] offset:2560
	global_load_dwordx2 v[108:109], v1, s[16:17] offset:3072
	global_load_dwordx2 v[110:111], v1, s[16:17] offset:3584
	s_waitcnt vmcnt(24)
	v_lshlrev_b32_e32 v112, 16, v48
	v_and_b32_e32 v113, 0xffff0000, v48
	v_lshlrev_b32_e32 v114, 16, v49
	v_and_b32_e32 v115, 0xffff0000, v49
	v_mul_f32_e32 v10, v113, v113
	v_mul_f32_e32 v247, v115, v115
	v_fmac_f32_e32 v10, v112, v112
	v_fmac_f32_e32 v247, v114, v114
	v_add_f32_e32 v10, v10, v247
	v_lshlrev_b32_e32 v116, 16, v50
	v_and_b32_e32 v117, 0xffff0000, v50
	v_lshlrev_b32_e32 v118, 16, v51
	v_and_b32_e32 v119, 0xffff0000, v51
	v_mul_f32_e32 v245, v117, v117
	v_mul_f32_e32 v247, v119, v119
	v_fmac_f32_e32 v245, v116, v116
	v_fmac_f32_e32 v247, v118, v118
	v_add_f32_e32 v245, v245, v247
	v_add_f32_e32 v10, v10, v245
	v_lshlrev_b32_e32 v120, 16, v52
	v_and_b32_e32 v121, 0xffff0000, v52
	v_lshlrev_b32_e32 v122, 16, v53
	v_and_b32_e32 v123, 0xffff0000, v53
	v_mul_f32_e32 v245, v121, v121
	v_mul_f32_e32 v247, v123, v123
	v_fmac_f32_e32 v245, v120, v120
	v_fmac_f32_e32 v247, v122, v122
	v_add_f32_e32 v245, v245, v247
	v_add_f32_e32 v10, v10, v245
	v_lshlrev_b32_e32 v124, 16, v54
	v_and_b32_e32 v125, 0xffff0000, v54
	v_lshlrev_b32_e32 v126, 16, v55
	v_and_b32_e32 v127, 0xffff0000, v55
	v_mul_f32_e32 v245, v125, v125
	v_mul_f32_e32 v247, v127, v127
	v_fmac_f32_e32 v245, v124, v124
	v_fmac_f32_e32 v247, v126, v126
	v_add_f32_e32 v245, v245, v247
	v_add_f32_e32 v10, v10, v245
	v_lshlrev_b32_e32 v128, 16, v56
	v_and_b32_e32 v129, 0xffff0000, v56
	v_lshlrev_b32_e32 v130, 16, v57
	v_and_b32_e32 v131, 0xffff0000, v57
	v_mul_f32_e32 v245, v129, v129
	v_mul_f32_e32 v247, v131, v131
	v_fmac_f32_e32 v245, v128, v128
	v_fmac_f32_e32 v247, v130, v130
	v_add_f32_e32 v245, v245, v247
	v_add_f32_e32 v10, v10, v245
	v_lshlrev_b32_e32 v132, 16, v58
	v_and_b32_e32 v133, 0xffff0000, v58
	v_lshlrev_b32_e32 v134, 16, v59
	v_and_b32_e32 v135, 0xffff0000, v59
	v_mul_f32_e32 v245, v133, v133
	v_mul_f32_e32 v247, v135, v135
	v_fmac_f32_e32 v245, v132, v132
	v_fmac_f32_e32 v247, v134, v134
	v_add_f32_e32 v245, v245, v247
	v_add_f32_e32 v10, v10, v245
	v_lshlrev_b32_e32 v136, 16, v60
	v_and_b32_e32 v137, 0xffff0000, v60
	v_lshlrev_b32_e32 v138, 16, v61
	v_and_b32_e32 v139, 0xffff0000, v61
	v_mul_f32_e32 v245, v137, v137
	v_mul_f32_e32 v247, v139, v139
	v_fmac_f32_e32 v245, v136, v136
	v_fmac_f32_e32 v247, v138, v138
	v_add_f32_e32 v245, v245, v247
	v_add_f32_e32 v10, v10, v245
	v_lshlrev_b32_e32 v140, 16, v62
	v_and_b32_e32 v141, 0xffff0000, v62
	v_lshlrev_b32_e32 v142, 16, v63
	v_and_b32_e32 v143, 0xffff0000, v63
	v_mul_f32_e32 v245, v141, v141
	v_mul_f32_e32 v247, v143, v143
	v_fmac_f32_e32 v245, v140, v140
	v_fmac_f32_e32 v247, v142, v142
	v_add_f32_e32 v245, v245, v247
	v_add_f32_e32 v10, v10, v245
	s_waitcnt vmcnt(16)
; __device__ __forceinline__ float bf_lo(unsigned w) { return __uint_as_float(w << 16); }
; __device__ __forceinline__ float bf_hi(unsigned w) { return __uint_as_float(w & 0xffff0000u); }
; __global__ void __launch_bounds__(NTHR, 2) fwd_kernel(Args a) {
;     ...
;         else { const u32x2* xr = (const u32x2*)(XN + (size_t)m * DM) + lane; f32x4 v[8]; float sq = 0.f;
; #pragma unroll
;             for (int j = 0; j < 8; ++j) { const u32x2 w = xr[64 * j]; v[j] = (f32x4){bf_lo(w.x), bf_hi(w.x), bf_lo(w.y), bf_hi(w.y)}; sq += (v[j].x * v[j].x + v[j].y * v[j].y) + (v[j].z * v[j].z + v[j].w * v[j].w); }
;             const float rstd = rsqrtf(wave_sum(sq) * (1.f / DM) + EPS); const f32x4* gr = (const f32x4*)final_norm_g + lane; f32x4* o = (f32x4*)(out + O_YP + (size_t)m * DM) + lane;
; #pragma unroll
;             for (int j = 0; j < 8; ++j) o[64 * j] = v[j] * rstd * gr[64 * j]; } }
	v_lshlrev_b32_e32 v144, 16, v64
	v_and_b32_e32 v145, 0xffff0000, v64
	v_lshlrev_b32_e32 v146, 16, v65
	v_and_b32_e32 v147, 0xffff0000, v65
	v_mul_f32_e32 v12, v145, v145
	v_mul_f32_e32 v247, v147, v147
	v_fmac_f32_e32 v12, v144, v144
	v_fmac_f32_e32 v247, v146, v146
	v_add_f32_e32 v12, v12, v247
	v_lshlrev_b32_e32 v148, 16, v66
	v_and_b32_e32 v149, 0xffff0000, v66
	v_lshlrev_b32_e32 v150, 16, v67
	v_and_b32_e32 v151, 0xffff0000, v67
	v_mul_f32_e32 v245, v149, v149
	v_mul_f32_e32 v247, v151, v151
	v_fmac_f32_e32 v245, v148, v148
	v_fmac_f32_e32 v247, v150, v150
	v_add_f32_e32 v245, v245, v247
	v_add_f32_e32 v12, v12, v245
	v_lshlrev_b32_e32 v152, 16, v68
	v_and_b32_e32 v153, 0xffff0000, v68
	v_lshlrev_b32_e32 v154, 16, v69
	v_and_b32_e32 v155, 0xffff0000, v69
	v_mul_f32_e32 v245, v153, v153
	v_mul_f32_e32 v247, v155, v155
	v_fmac_f32_e32 v245, v152, v152
	v_fmac_f32_e32 v247, v154, v154
	v_add_f32_e32 v245, v245, v247
	v_add_f32_e32 v12, v12, v245
	v_lshlrev_b32_e32 v156, 16, v70
	v_and_b32_e32 v157, 0xffff0000, v70
	v_lshlrev_b32_e32 v158, 16, v71
	v_and_b32_e32 v159, 0xffff0000, v71
	v_mul_f32_e32 v245, v157, v157
	v_mul_f32_e32 v247, v159, v159
	v_fmac_f32_e32 v245, v156, v156
	v_fmac_f32_e32 v247, v158, v158
	v_add_f32_e32 v245, v245, v247
	v_add_f32_e32 v12, v12, v245
	v_lshlrev_b32_e32 v160, 16, v72
	v_and_b32_e32 v161, 0xffff0000, v72
	v_lshlrev_b32_e32 v162, 16, v73
	v_and_b32_e32 v163, 0xffff0000, v73
	v_mul_f32_e32 v245, v161, v161
	v_mul_f32_e32 v247, v163, v163
	v_fmac_f32_e32 v245, v160, v160
	v_fmac_f32_e32 v247, v162, v162
	v_add_f32_e32 v245, v245, v247
	v_add_f32_e32 v12, v12, v245
	v_lshlrev_b32_e32 v164, 16, v74
	v_and_b32_e32 v165, 0xffff0000, v74
	v_lshlrev_b32_e32 v166, 16, v75
	v_and_b32_e32 v167, 0xffff0000, v75
	v_mul_f32_e32 v245, v165, v165
	v_mul_f32_e32 v247, v167, v167
	v_fmac_f32_e32 v245, v164, v164
	v_fmac_f32_e32 v247, v166, v166
	v_add_f32_e32 v245, v245, v247
	v_add_f32_e32 v12, v12, v245
	v_lshlrev_b32_e32 v168, 16, v76
	v_and_b32_e32 v169, 0xffff0000, v76
	v_lshlrev_b32_e32 v170, 16, v77
	v_and_b32_e32 v171, 0xffff0000, v77
	v_mul_f32_e32 v245, v169, v169
	v_mul_f32_e32 v247, v171, v171
	v_fmac_f32_e32 v245, v168, v168
	v_fmac_f32_e32 v247, v170, v170
	v_add_f32_e32 v245, v245, v247
	v_add_f32_e32 v12, v12, v245
	v_lshlrev_b32_e32 v172, 16, v78
	v_and_b32_e32 v173, 0xffff0000, v78
	v_lshlrev_b32_e32 v174, 16, v79
	v_and_b32_e32 v175, 0xffff0000, v79
	v_mul_f32_e32 v245, v173, v173
	v_mul_f32_e32 v247, v175, v175
	v_fmac_f32_e32 v245, v172, v172
	v_fmac_f32_e32 v247, v174, v174
	v_add_f32_e32 v245, v245, v247
	v_add_f32_e32 v12, v12, v245
	s_waitcnt vmcnt(8)
	v_lshlrev_b32_e32 v176, 16, v80
	v_and_b32_e32 v177, 0xffff0000, v80
	v_lshlrev_b32_e32 v178, 16, v81
	v_and_b32_e32 v179, 0xffff0000, v81
	v_mul_f32_e32 v14, v177, v177
	v_mul_f32_e32 v247, v179, v179
	v_fmac_f32_e32 v14, v176, v176
	v_fmac_f32_e32 v247, v178, v178
	v_add_f32_e32 v14, v14, v247
	v_lshlrev_b32_e32 v180, 16, v82
	v_and_b32_e32 v181, 0xffff0000, v82
	v_lshlrev_b32_e32 v182, 16, v83
	v_and_b32_e32 v183, 0xffff0000, v83
	v_mul_f32_e32 v245, v181, v181
	v_mul_f32_e32 v247, v183, v183
	v_fmac_f32_e32 v245, v180, v180
	v_fmac_f32_e32 v247, v182, v182
	v_add_f32_e32 v245, v245, v247
	v_add_f32_e32 v14, v14, v245
	v_lshlrev_b32_e32 v184, 16, v84
	v_and_b32_e32 v185, 0xffff0000, v84
	v_lshlrev_b32_e32 v186, 16, v85
	v_and_b32_e32 v187, 0xffff0000, v85
	v_mul_f32_e32 v245, v185, v185
	v_mul_f32_e32 v247, v187, v187
	v_fmac_f32_e32 v245, v184, v184
	v_fmac_f32_e32 v247, v186, v186
	v_add_f32_e32 v245, v245, v247
	v_add_f32_e32 v14, v14, v245
	v_lshlrev_b32_e32 v188, 16, v86
	v_and_b32_e32 v189, 0xffff0000, v86
	v_lshlrev_b32_e32 v190, 16, v87
	v_and_b32_e32 v191, 0xffff0000, v87
	v_mul_f32_e32 v245, v189, v189
	v_mul_f32_e32 v247, v191, v191
	v_fmac_f32_e32 v245, v188, v188
	v_fmac_f32_e32 v247, v190, v190
	v_add_f32_e32 v245, v245, v247
	v_add_f32_e32 v14, v14, v245
	v_lshlrev_b32_e32 v192, 16, v88
	v_and_b32_e32 v193, 0xffff0000, v88
	v_lshlrev_b32_e32 v194, 16, v89
	v_and_b32_e32 v195, 0xffff0000, v89
	v_mul_f32_e32 v245, v193, v193
	v_mul_f32_e32 v247, v195, v195
	v_fmac_f32_e32 v245, v192, v192
	v_fmac_f32_e32 v247, v194, v194
	v_add_f32_e32 v245, v245, v247
	v_add_f32_e32 v14, v14, v245
	v_lshlrev_b32_e32 v196, 16, v90
	v_and_b32_e32 v197, 0xffff0000, v90
	v_lshlrev_b32_e32 v198, 16, v91
	v_and_b32_e32 v199, 0xffff0000, v91
	v_mul_f32_e32 v245, v197, v197
	v_mul_f32_e32 v247, v199, v199
	v_fmac_f32_e32 v245, v196, v196
	v_fmac_f32_e32 v247, v198, v198
	v_add_f32_e32 v245, v245, v247
	v_add_f32_e32 v14, v14, v245
	v_lshlrev_b32_e32 v200, 16, v92
	v_and_b32_e32 v201, 0xffff0000, v92
	v_lshlrev_b32_e32 v202, 16, v93
	v_and_b32_e32 v203, 0xffff0000, v93
	v_mul_f32_e32 v245, v201, v201
	v_mul_f32_e32 v247, v203, v203
	v_fmac_f32_e32 v245, v200, v200
	v_fmac_f32_e32 v247, v202, v202
	v_add_f32_e32 v245, v245, v247
	v_add_f32_e32 v14, v14, v245
	v_lshlrev_b32_e32 v204, 16, v94
	v_and_b32_e32 v205, 0xffff0000, v94
	v_lshlrev_b32_e32 v206, 16, v95
	v_and_b32_e32 v207, 0xffff0000, v95
	v_mul_f32_e32 v245, v205, v205
	v_mul_f32_e32 v247, v207, v207
	v_fmac_f32_e32 v245, v204, v204
	v_fmac_f32_e32 v247, v206, v206
	v_add_f32_e32 v245, v245, v247
	v_add_f32_e32 v14, v14, v245
	s_waitcnt vmcnt(0)
; __device__ __forceinline__ float bf_lo(unsigned w) { return __uint_as_float(w << 16); }
; __device__ __forceinline__ float bf_hi(unsigned w) { return __uint_as_float(w & 0xffff0000u); }
; __global__ void __launch_bounds__(NTHR, 2) fwd_kernel(Args a) {
;     ...
;         else { const u32x2* xr = (const u32x2*)(XN + (size_t)m * DM) + lane; f32x4 v[8]; float sq = 0.f;
; #pragma unroll
;             for (int j = 0; j < 8; ++j) { const u32x2 w = xr[64 * j]; v[j] = (f32x4){bf_lo(w.x), bf_hi(w.x), bf_lo(w.y), bf_hi(w.y)}; sq += (v[j].x * v[j].x + v[j].y * v[j].y) + (v[j].z * v[j].z + v[j].w * v[j].w); }
;             const float rstd = rsqrtf(wave_sum(sq) * (1.f / DM) + EPS); const f32x4* gr = (const f32x4*)final_norm_g + lane; f32x4* o = (f32x4*)(out + O_YP + (size_t)m * DM) + lane;
; #pragma unroll
;             for (int j = 0; j < 8; ++j) o[64 * j] = v[j] * rstd * gr[64 * j]; } }
	v_lshlrev_b32_e32 v208, 16, v96
	v_and_b32_e32 v209, 0xffff0000, v96
	v_lshlrev_b32_e32 v210, 16, v97
	v_and_b32_e32 v211, 0xffff0000, v97
	v_mul_f32_e32 v240, v209, v209
	v_mul_f32_e32 v247, v211, v211
	v_fmac_f32_e32 v240, v208, v208
	v_fmac_f32_e32 v247, v210, v210
	v_add_f32_e32 v240, v240, v247
	v_lshlrev_b32_e32 v212, 16, v98
	v_and_b32_e32 v213, 0xffff0000, v98
	v_lshlrev_b32_e32 v214, 16, v99
	v_and_b32_e32 v215, 0xffff0000, v99
	v_mul_f32_e32 v245, v213, v213
	v_mul_f32_e32 v247, v215, v215
	v_fmac_f32_e32 v245, v212, v212
	v_fmac_f32_e32 v247, v214, v214
	v_add_f32_e32 v245, v245, v247
	v_add_f32_e32 v240, v240, v245
	v_lshlrev_b32_e32 v216, 16, v100
	v_and_b32_e32 v217, 0xffff0000, v100
	v_lshlrev_b32_e32 v218, 16, v101
	v_and_b32_e32 v219, 0xffff0000, v101
	v_mul_f32_e32 v245, v217, v217
	v_mul_f32_e32 v247, v219, v219
	v_fmac_f32_e32 v245, v216, v216
	v_fmac_f32_e32 v247, v218, v218
	v_add_f32_e32 v245, v245, v247
	v_add_f32_e32 v240, v240, v245
	v_lshlrev_b32_e32 v220, 16, v102
	v_and_b32_e32 v221, 0xffff0000, v102
	v_lshlrev_b32_e32 v222, 16, v103
	v_and_b32_e32 v223, 0xffff0000, v103
	v_mul_f32_e32 v245, v221, v221
	v_mul_f32_e32 v247, v223, v223
	v_fmac_f32_e32 v245, v220, v220
	v_fmac_f32_e32 v247, v222, v222
	v_add_f32_e32 v245, v245, v247
	v_add_f32_e32 v240, v240, v245
	v_lshlrev_b32_e32 v224, 16, v104
	v_and_b32_e32 v225, 0xffff0000, v104
	v_lshlrev_b32_e32 v226, 16, v105
	v_and_b32_e32 v227, 0xffff0000, v105
	v_mul_f32_e32 v245, v225, v225
	v_mul_f32_e32 v247, v227, v227
	v_fmac_f32_e32 v245, v224, v224
	v_fmac_f32_e32 v247, v226, v226
	v_add_f32_e32 v245, v245, v247
	v_add_f32_e32 v240, v240, v245
	v_lshlrev_b32_e32 v228, 16, v106
	v_and_b32_e32 v229, 0xffff0000, v106
	v_lshlrev_b32_e32 v230, 16, v107
	v_and_b32_e32 v231, 0xffff0000, v107
	v_mul_f32_e32 v245, v229, v229
	v_mul_f32_e32 v247, v231, v231
	v_fmac_f32_e32 v245, v228, v228
	v_fmac_f32_e32 v247, v230, v230
	v_add_f32_e32 v245, v245, v247
	v_add_f32_e32 v240, v240, v245
	v_lshlrev_b32_e32 v232, 16, v108
	v_and_b32_e32 v233, 0xffff0000, v108
	v_lshlrev_b32_e32 v234, 16, v109
	v_and_b32_e32 v235, 0xffff0000, v109
	v_mul_f32_e32 v245, v233, v233
	v_mul_f32_e32 v247, v235, v235
	v_fmac_f32_e32 v245, v232, v232
	v_fmac_f32_e32 v247, v234, v234
	v_add_f32_e32 v245, v245, v247
	v_add_f32_e32 v240, v240, v245
	v_lshlrev_b32_e32 v236, 16, v110
	v_and_b32_e32 v237, 0xffff0000, v110
	v_lshlrev_b32_e32 v238, 16, v111
	v_and_b32_e32 v239, 0xffff0000, v111
	v_mul_f32_e32 v245, v237, v237
	v_mul_f32_e32 v247, v239, v239
	v_fmac_f32_e32 v245, v236, v236
	v_fmac_f32_e32 v247, v238, v238
	v_add_f32_e32 v245, v245, v247
	v_add_f32_e32 v240, v240, v245
	ds_bpermute_b32 v241, v3, v10
	ds_bpermute_b32 v242, v3, v12
	ds_bpermute_b32 v243, v3, v14
	ds_bpermute_b32 v244, v3, v240
	s_waitcnt lgkmcnt(0)
	v_add_f32_e32 v10, v10, v241
	v_add_f32_e32 v12, v12, v242
	v_add_f32_e32 v14, v14, v243
	v_add_f32_e32 v240, v240, v244
	ds_bpermute_b32 v241, v4, v10
	ds_bpermute_b32 v242, v4, v12
	ds_bpermute_b32 v243, v4, v14
	ds_bpermute_b32 v244, v4, v240
	s_waitcnt lgkmcnt(0)
	v_add_f32_e32 v10, v10, v241
	v_add_f32_e32 v12, v12, v242
	v_add_f32_e32 v14, v14, v243
	v_add_f32_e32 v240, v240, v244
	ds_bpermute_b32 v241, v5, v10
	ds_bpermute_b32 v242, v5, v12
	ds_bpermute_b32 v243, v5, v14
	ds_bpermute_b32 v244, v5, v240
	s_waitcnt lgkmcnt(0)
	v_add_f32_e32 v10, v10, v241
	v_add_f32_e32 v12, v12, v242
	v_add_f32_e32 v14, v14, v243
	v_add_f32_e32 v240, v240, v244
	ds_bpermute_b32 v241, v6, v10
	ds_bpermute_b32 v242, v6, v12
	ds_bpermute_b32 v243, v6, v14
	ds_bpermute_b32 v244, v6, v240
	s_waitcnt lgkmcnt(0)
	v_add_f32_e32 v10, v10, v241
	v_add_f32_e32 v12, v12, v242
	v_add_f32_e32 v14, v14, v243
	v_add_f32_e32 v240, v240, v244
	ds_bpermute_b32 v241, v7, v10
	ds_bpermute_b32 v242, v7, v12
	ds_bpermute_b32 v243, v7, v14
	ds_bpermute_b32 v244, v7, v240
	s_waitcnt lgkmcnt(0)
	v_add_f32_e32 v10, v10, v241
	v_add_f32_e32 v12, v12, v242
	v_add_f32_e32 v14, v14, v243
	v_add_f32_e32 v240, v240, v244
	ds_bpermute_b32 v241, v8, v10
	ds_bpermute_b32 v242, v8, v12
	ds_bpermute_b32 v243, v8, v14
	ds_bpermute_b32 v244, v8, v240
	s_waitcnt lgkmcnt(0)
	v_add_f32_e32 v10, v10, v241
	v_add_f32_e32 v12, v12, v242
	v_add_f32_e32 v14, v14, v243
	v_add_f32_e32 v240, v240, v244
	v_fmamk_f32 v10, v10, 0x3a000000, v9
	v_mul_f32_e32 v245, 0x4b800000, v10
	v_cmp_gt_f32_e32 vcc, s12, v10
	s_nop 1
	v_cndmask_b32_e32 v10, v10, v245, vcc
	v_rsq_f32_e32 v10, v10
	s_nop 0
	v_mul_f32_e32 v245, 0x45800000, v10
	v_cndmask_b32_e32 v10, v10, v245, vcc
	v_fmamk_f32 v12, v12, 0x3a000000, v9
	v_mul_f32_e32 v245, 0x4b800000, v12
	v_cmp_gt_f32_e32 vcc, s12, v12
	s_nop 1
	v_cndmask_b32_e32 v12, v12, v245, vcc
	v_rsq_f32_e32 v12, v12
	s_nop 0
	v_mul_f32_e32 v245, 0x45800000, v12
	v_cndmask_b32_e32 v12, v12, v245, vcc
	v_fmamk_f32 v14, v14, 0x3a000000, v9
	v_mul_f32_e32 v245, 0x4b800000, v14
	v_cmp_gt_f32_e32 vcc, s12, v14
	s_nop 1
	v_cndmask_b32_e32 v14, v14, v245, vcc
	v_rsq_f32_e32 v14, v14
	s_nop 0
	v_mul_f32_e32 v245, 0x45800000, v14
	v_cndmask_b32_e32 v14, v14, v245, vcc
	v_fmamk_f32 v240, v240, 0x3a000000, v9
	v_mul_f32_e32 v245, 0x4b800000, v240
	v_cmp_gt_f32_e32 vcc, s12, v240
	s_nop 1
	v_cndmask_b32_e32 v240, v240, v245, vcc
	v_rsq_f32_e32 v240, v240
	s_nop 0
	v_mul_f32_e32 v245, 0x45800000, v240
	v_cndmask_b32_e32 v240, v240, v245, vcc
	s_waitcnt vmcnt(0)
; __device__ __forceinline__ float bf_lo(unsigned w) { return __uint_as_float(w << 16); }
; __device__ __forceinline__ float bf_hi(unsigned w) { return __uint_as_float(w & 0xffff0000u); }
; __global__ void __launch_bounds__(NTHR, 2) fwd_kernel(Args a) {
;     ...
;         else { const u32x2* xr = (const u32x2*)(XN + (size_t)m * DM) + lane; f32x4 v[8]; float sq = 0.f;
; #pragma unroll
;             for (int j = 0; j < 8; ++j) { const u32x2 w = xr[64 * j]; v[j] = (f32x4){bf_lo(w.x), bf_hi(w.x), bf_lo(w.y), bf_hi(w.y)}; sq += (v[j].x * v[j].x + v[j].y * v[j].y) + (v[j].z * v[j].z + v[j].w * v[j].w); }
;             const float rstd = rsqrtf(wave_sum(sq) * (1.f / DM) + EPS); const f32x4* gr = (const f32x4*)final_norm_g + lane; f32x4* o = (f32x4*)(out + O_YP + (size_t)m * DM) + lane;
; #pragma unroll
;             for (int j = 0; j < 8; ++j) o[64 * j] = v[j] * rstd * gr[64 * j]; } }
	s_lshl_b32 s16, s20, 13
	s_add_u32 s16, s6, s16
	s_addc_u32 s17, s7, 0
	v_pk_mul_f32 v[112:113], v[10:11], v[112:113] op_sel_hi:[0,1]
	v_pk_mul_f32 v[114:115], v[10:11], v[114:115] op_sel_hi:[0,1]
	v_pk_mul_f32 v[112:113], v[112:113], v[16:17]
	v_pk_mul_f32 v[114:115], v[114:115], v[18:19]
	global_store_dwordx4 v0, v[112:115], s[16:17]
	v_pk_mul_f32 v[116:117], v[10:11], v[116:117] op_sel_hi:[0,1]
	v_pk_mul_f32 v[118:119], v[10:11], v[118:119] op_sel_hi:[0,1]
	v_pk_mul_f32 v[116:117], v[116:117], v[20:21]
	v_pk_mul_f32 v[118:119], v[118:119], v[22:23]
	global_store_dwordx4 v0, v[116:119], s[16:17] offset:1024
	v_pk_mul_f32 v[120:121], v[10:11], v[120:121] op_sel_hi:[0,1]
	v_pk_mul_f32 v[122:123], v[10:11], v[122:123] op_sel_hi:[0,1]
	v_pk_mul_f32 v[120:121], v[120:121], v[24:25]
	v_pk_mul_f32 v[122:123], v[122:123], v[26:27]
	global_store_dwordx4 v0, v[120:123], s[16:17] offset:2048
	v_pk_mul_f32 v[124:125], v[10:11], v[124:125] op_sel_hi:[0,1]
	v_pk_mul_f32 v[126:127], v[10:11], v[126:127] op_sel_hi:[0,1]
	v_pk_mul_f32 v[124:125], v[124:125], v[28:29]
	v_pk_mul_f32 v[126:127], v[126:127], v[30:31]
	global_store_dwordx4 v0, v[124:127], s[16:17] offset:3072
	v_pk_mul_f32 v[128:129], v[10:11], v[128:129] op_sel_hi:[0,1]
	v_pk_mul_f32 v[130:131], v[10:11], v[130:131] op_sel_hi:[0,1]
	v_pk_mul_f32 v[128:129], v[128:129], v[32:33]
	v_pk_mul_f32 v[130:131], v[130:131], v[34:35]
	global_store_dwordx4 v2, v[128:131], s[16:17]
	v_pk_mul_f32 v[132:133], v[10:11], v[132:133] op_sel_hi:[0,1]
	v_pk_mul_f32 v[134:135], v[10:11], v[134:135] op_sel_hi:[0,1]
	v_pk_mul_f32 v[132:133], v[132:133], v[36:37]
	v_pk_mul_f32 v[134:135], v[134:135], v[38:39]
	global_store_dwordx4 v2, v[132:135], s[16:17] offset:1024
	v_pk_mul_f32 v[136:137], v[10:11], v[136:137] op_sel_hi:[0,1]
	v_pk_mul_f32 v[138:139], v[10:11], v[138:139] op_sel_hi:[0,1]
	v_pk_mul_f32 v[136:137], v[136:137], v[40:41]
	v_pk_mul_f32 v[138:139], v[138:139], v[42:43]
	global_store_dwordx4 v2, v[136:139], s[16:17] offset:2048
	v_pk_mul_f32 v[140:141], v[10:11], v[140:141] op_sel_hi:[0,1]
	v_pk_mul_f32 v[142:143], v[10:11], v[142:143] op_sel_hi:[0,1]
	v_pk_mul_f32 v[140:141], v[140:141], v[44:45]
	v_pk_mul_f32 v[142:143], v[142:143], v[46:47]
	global_store_dwordx4 v2, v[140:143], s[16:17] offset:3072
	s_cmp_eq_u32 s25, 0
	s_cbranch_scc1 .Lfin_skip_1
	s_lshl_b32 s16, s21, 13
	s_add_u32 s16, s6, s16
	s_addc_u32 s17, s7, 0
	v_pk_mul_f32 v[144:145], v[12:13], v[144:145] op_sel_hi:[0,1]
	v_pk_mul_f32 v[146:147], v[12:13], v[146:147] op_sel_hi:[0,1]
	v_pk_mul_f32 v[144:145], v[144:145], v[16:17]
	v_pk_mul_f32 v[146:147], v[146:147], v[18:19]
	global_store_dwordx4 v0, v[144:147], s[16:17]
	v_pk_mul_f32 v[148:149], v[12:13], v[148:149] op_sel_hi:[0,1]
	v_pk_mul_f32 v[150:151], v[12:13], v[150:151] op_sel_hi:[0,1]
	v_pk_mul_f32 v[148:149], v[148:149], v[20:21]
	v_pk_mul_f32 v[150:151], v[150:151], v[22:23]
	global_store_dwordx4 v0, v[148:151], s[16:17] offset:1024
	v_pk_mul_f32 v[152:153], v[12:13], v[152:153] op_sel_hi:[0,1]
	v_pk_mul_f32 v[154:155], v[12:13], v[154:155] op_sel_hi:[0,1]
	v_pk_mul_f32 v[152:153], v[152:153], v[24:25]
	v_pk_mul_f32 v[154:155], v[154:155], v[26:27]
	global_store_dwordx4 v0, v[152:155], s[16:17] offset:2048
	v_pk_mul_f32 v[156:157], v[12:13], v[156:157] op_sel_hi:[0,1]
	v_pk_mul_f32 v[158:159], v[12:13], v[158:159] op_sel_hi:[0,1]
	v_pk_mul_f32 v[156:157], v[156:157], v[28:29]
	v_pk_mul_f32 v[158:159], v[158:159], v[30:31]
	global_store_dwordx4 v0, v[156:159], s[16:17] offset:3072
	v_pk_mul_f32 v[160:161], v[12:13], v[160:161] op_sel_hi:[0,1]
	v_pk_mul_f32 v[162:163], v[12:13], v[162:163] op_sel_hi:[0,1]
	v_pk_mul_f32 v[160:161], v[160:161], v[32:33]
	v_pk_mul_f32 v[162:163], v[162:163], v[34:35]
	global_store_dwordx4 v2, v[160:163], s[16:17]
	v_pk_mul_f32 v[164:165], v[12:13], v[164:165] op_sel_hi:[0,1]
	v_pk_mul_f32 v[166:167], v[12:13], v[166:167] op_sel_hi:[0,1]
	v_pk_mul_f32 v[164:165], v[164:165], v[36:37]
	v_pk_mul_f32 v[166:167], v[166:167], v[38:39]
	global_store_dwordx4 v2, v[164:167], s[16:17] offset:1024
	v_pk_mul_f32 v[168:169], v[12:13], v[168:169] op_sel_hi:[0,1]
	v_pk_mul_f32 v[170:171], v[12:13], v[170:171] op_sel_hi:[0,1]
	v_pk_mul_f32 v[168:169], v[168:169], v[40:41]
	v_pk_mul_f32 v[170:171], v[170:171], v[42:43]
	global_store_dwordx4 v2, v[168:171], s[16:17] offset:2048
	v_pk_mul_f32 v[172:173], v[12:13], v[172:173] op_sel_hi:[0,1]
	v_pk_mul_f32 v[174:175], v[12:13], v[174:175] op_sel_hi:[0,1]
	v_pk_mul_f32 v[172:173], v[172:173], v[44:45]
	v_pk_mul_f32 v[174:175], v[174:175], v[46:47]
	global_store_dwordx4 v2, v[172:175], s[16:17] offset:3072
; __device__ __forceinline__ float bf_lo(unsigned w) { return __uint_as_float(w << 16); }
; __device__ __forceinline__ float bf_hi(unsigned w) { return __uint_as_float(w & 0xffff0000u); }
; __global__ void __launch_bounds__(NTHR, 2) fwd_kernel(Args a) {
;     ...
;         else { const u32x2* xr = (const u32x2*)(XN + (size_t)m * DM) + lane; f32x4 v[8]; float sq = 0.f;
; #pragma unroll
;             for (int j = 0; j < 8; ++j) { const u32x2 w = xr[64 * j]; v[j] = (f32x4){bf_lo(w.x), bf_hi(w.x), bf_lo(w.y), bf_hi(w.y)}; sq += (v[j].x * v[j].x + v[j].y * v[j].y) + (v[j].z * v[j].z + v[j].w * v[j].w); }
;             const float rstd = rsqrtf(wave_sum(sq) * (1.f / DM) + EPS); const f32x4* gr = (const f32x4*)final_norm_g + lane; f32x4* o = (f32x4*)(out + O_YP + (size_t)m * DM) + lane;
; #pragma unroll
;             for (int j = 0; j < 8; ++j) o[64 * j] = v[j] * rstd * gr[64 * j]; } }
.Lfin_skip_1:
	s_cmp_eq_u32 s26, 0
	s_cbranch_scc1 .Lfin_skip_2
	s_lshl_b32 s16, s22, 13
	s_add_u32 s16, s6, s16
	s_addc_u32 s17, s7, 0
	v_pk_mul_f32 v[176:177], v[14:15], v[176:177] op_sel_hi:[0,1]
	v_pk_mul_f32 v[178:179], v[14:15], v[178:179] op_sel_hi:[0,1]
	v_pk_mul_f32 v[176:177], v[176:177], v[16:17]
	v_pk_mul_f32 v[178:179], v[178:179], v[18:19]
	global_store_dwordx4 v0, v[176:179], s[16:17]
	v_pk_mul_f32 v[180:181], v[14:15], v[180:181] op_sel_hi:[0,1]
	v_pk_mul_f32 v[182:183], v[14:15], v[182:183] op_sel_hi:[0,1]
	v_pk_mul_f32 v[180:181], v[180:181], v[20:21]
	v_pk_mul_f32 v[182:183], v[182:183], v[22:23]
	global_store_dwordx4 v0, v[180:183], s[16:17] offset:1024
	v_pk_mul_f32 v[184:185], v[14:15], v[184:185] op_sel_hi:[0,1]
	v_pk_mul_f32 v[186:187], v[14:15], v[186:187] op_sel_hi:[0,1]
	v_pk_mul_f32 v[184:185], v[184:185], v[24:25]
	v_pk_mul_f32 v[186:187], v[186:187], v[26:27]
	global_store_dwordx4 v0, v[184:187], s[16:17] offset:2048
	v_pk_mul_f32 v[188:189], v[14:15], v[188:189] op_sel_hi:[0,1]
	v_pk_mul_f32 v[190:191], v[14:15], v[190:191] op_sel_hi:[0,1]
	v_pk_mul_f32 v[188:189], v[188:189], v[28:29]
	v_pk_mul_f32 v[190:191], v[190:191], v[30:31]
	global_store_dwordx4 v0, v[188:191], s[16:17] offset:3072
	v_pk_mul_f32 v[192:193], v[14:15], v[192:193] op_sel_hi:[0,1]
	v_pk_mul_f32 v[194:195], v[14:15], v[194:195] op_sel_hi:[0,1]
	v_pk_mul_f32 v[192:193], v[192:193], v[32:33]
	v_pk_mul_f32 v[194:195], v[194:195], v[34:35]
	global_store_dwordx4 v2, v[192:195], s[16:17]
	v_pk_mul_f32 v[196:197], v[14:15], v[196:197] op_sel_hi:[0,1]
	v_pk_mul_f32 v[198:199], v[14:15], v[198:199] op_sel_hi:[0,1]
	v_pk_mul_f32 v[196:197], v[196:197], v[36:37]
	v_pk_mul_f32 v[198:199], v[198:199], v[38:39]
	global_store_dwordx4 v2, v[196:199], s[16:17] offset:1024
	v_pk_mul_f32 v[200:201], v[14:15], v[200:201] op_sel_hi:[0,1]
	v_pk_mul_f32 v[202:203], v[14:15], v[202:203] op_sel_hi:[0,1]
	v_pk_mul_f32 v[200:201], v[200:201], v[40:41]
	v_pk_mul_f32 v[202:203], v[202:203], v[42:43]
	global_store_dwordx4 v2, v[200:203], s[16:17] offset:2048
	v_pk_mul_f32 v[204:205], v[14:15], v[204:205] op_sel_hi:[0,1]
	v_pk_mul_f32 v[206:207], v[14:15], v[206:207] op_sel_hi:[0,1]
	v_pk_mul_f32 v[204:205], v[204:205], v[44:45]
	v_pk_mul_f32 v[206:207], v[206:207], v[46:47]
	global_store_dwordx4 v2, v[204:207], s[16:17] offset:3072
.Lfin_skip_2:
	s_cmp_eq_u32 s27, 0
	s_cbranch_scc1 .Lfin_skip_3
	s_lshl_b32 s16, s23, 13
	s_add_u32 s16, s6, s16
	s_addc_u32 s17, s7, 0
	v_pk_mul_f32 v[208:209], v[240:241], v[208:209] op_sel_hi:[0,1]
	v_pk_mul_f32 v[210:211], v[240:241], v[210:211] op_sel_hi:[0,1]
	v_pk_mul_f32 v[208:209], v[208:209], v[16:17]
	v_pk_mul_f32 v[210:211], v[210:211], v[18:19]
	global_store_dwordx4 v0, v[208:211], s[16:17]
	v_pk_mul_f32 v[212:213], v[240:241], v[212:213] op_sel_hi:[0,1]
	v_pk_mul_f32 v[214:215], v[240:241], v[214:215] op_sel_hi:[0,1]
	v_pk_mul_f32 v[212:213], v[212:213], v[20:21]
	v_pk_mul_f32 v[214:215], v[214:215], v[22:23]
	global_store_dwordx4 v0, v[212:215], s[16:17] offset:1024
	v_pk_mul_f32 v[216:217], v[240:241], v[216:217] op_sel_hi:[0,1]
	v_pk_mul_f32 v[218:219], v[240:241], v[218:219] op_sel_hi:[0,1]
	v_pk_mul_f32 v[216:217], v[216:217], v[24:25]
	v_pk_mul_f32 v[218:219], v[218:219], v[26:27]
	global_store_dwordx4 v0, v[216:219], s[16:17] offset:2048
	v_pk_mul_f32 v[220:221], v[240:241], v[220:221] op_sel_hi:[0,1]
	v_pk_mul_f32 v[222:223], v[240:241], v[222:223] op_sel_hi:[0,1]
	v_pk_mul_f32 v[220:221], v[220:221], v[28:29]
	v_pk_mul_f32 v[222:223], v[222:223], v[30:31]
	global_store_dwordx4 v0, v[220:223], s[16:17] offset:3072
	v_pk_mul_f32 v[224:225], v[240:241], v[224:225] op_sel_hi:[0,1]
	v_pk_mul_f32 v[226:227], v[240:241], v[226:227] op_sel_hi:[0,1]
	v_pk_mul_f32 v[224:225], v[224:225], v[32:33]
	v_pk_mul_f32 v[226:227], v[226:227], v[34:35]
	global_store_dwordx4 v2, v[224:227], s[16:17]
	v_pk_mul_f32 v[228:229], v[240:241], v[228:229] op_sel_hi:[0,1]
	v_pk_mul_f32 v[230:231], v[240:241], v[230:231] op_sel_hi:[0,1]
	v_pk_mul_f32 v[228:229], v[228:229], v[36:37]
	v_pk_mul_f32 v[230:231], v[230:231], v[38:39]
	global_store_dwordx4 v2, v[228:231], s[16:17] offset:1024
	v_pk_mul_f32 v[232:233], v[240:241], v[232:233] op_sel_hi:[0,1]
	v_pk_mul_f32 v[234:235], v[240:241], v[234:235] op_sel_hi:[0,1]
	v_pk_mul_f32 v[232:233], v[232:233], v[40:41]
	v_pk_mul_f32 v[234:235], v[234:235], v[42:43]
	global_store_dwordx4 v2, v[232:235], s[16:17] offset:2048
	v_pk_mul_f32 v[236:237], v[240:241], v[236:237] op_sel_hi:[0,1]
	v_pk_mul_f32 v[238:239], v[240:241], v[238:239] op_sel_hi:[0,1]
	v_pk_mul_f32 v[236:237], v[236:237], v[44:45]
	v_pk_mul_f32 v[238:239], v[238:239], v[46:47]
	global_store_dwordx4 v2, v[236:239], s[16:17] offset:3072
.Lfin_skip_3:
	s_add_i32 s3, s3, s15
	s_cmp_lt_u32 s3, 0x2000
	s_cbranch_scc1 .Lfin_prompt_loop
.Lfin_prompt_done:
	s_cmp_ge_u32 s14, 0x80
	s_cbranch_scc1 .Lfin_end
	s_waitcnt vmcnt(0)
; __device__ __forceinline__ void sample_assemble(const float* base, const float* XSP, int nsp, int s, float* xr, int lane) {
;     const f32x4* br = (const f32x4*)base + lane; f32x4* o = (f32x4*)xr + lane;
; #pragma unroll
;     for (int j = 0; j < 8; ++j) { f32x4 v = br[64 * j];
;         for (int sp = 0; sp < nsp; ++sp) v += *((const f32x4*)(XSP + ((size_t)sp * NS + s) * DM) + lane + 64 * j);
;         o[64 * j] = v; }
; }
; __global__ void __launch_bounds__(NTHR, 2) fwd_kernel(Args a) {
;     ...
;     for (int m = gw; m < MREAL; m += NGW) {
;         if (m >= MP) { sample_assemble(XR + (size_t)m * DM, XSP, 11, m - MP, XR + (size_t)m * DM, lane); rms_row_f32(XR + (size_t)m * DM, final_norm_g, out + O_YS + (size_t)(m - MP) * DM, lane); }
.Lfin_sample_loop:
	s_lshl_b32 s16, s14, 13
	s_add_u32 s18, s8, 0x216e4000
	s_addc_u32 s19, s9, 0
	s_add_u32 s18, s18, s16
	s_addc_u32 s19, s19, 0
	s_add_u32 s20, s8, 0x12700000
	s_addc_u32 s21, s9, 0
	s_add_u32 s20, s20, s16
	s_addc_u32 s21, s21, 0
	v_add_u32_e32 v48, 0x1000, v0
	global_load_dwordx4 v[82:85], v0, s[20:21]
	global_load_dwordx4 v[86:89], v0, s[18:19]
	s_add_u32 s22, s18, 0x100000
	s_addc_u32 s23, s19, 0
	global_load_dwordx4 v[90:93], v0, s[22:23]
	s_add_u32 s22, s18, 0x200000
	s_addc_u32 s23, s19, 0
	global_load_dwordx4 v[94:97], v0, s[22:23]
	s_add_u32 s22, s18, 0x300000
	s_addc_u32 s23, s19, 0
	global_load_dwordx4 v[98:101], v0, s[22:23]
	s_add_u32 s22, s18, 0x400000
	s_addc_u32 s23, s19, 0
	global_load_dwordx4 v[102:105], v0, s[22:23]
	s_add_u32 s22, s18, 0x500000
	s_addc_u32 s23, s19, 0
	global_load_dwordx4 v[106:109], v0, s[22:23]
	s_add_u32 s22, s18, 0x600000
	s_addc_u32 s23, s19, 0
	global_load_dwordx4 v[110:113], v0, s[22:23]
	s_add_u32 s22, s18, 0x700000
	s_addc_u32 s23, s19, 0
	global_load_dwordx4 v[114:117], v0, s[22:23]
	s_add_u32 s22, s18, 0x800000
	s_addc_u32 s23, s19, 0
	global_load_dwordx4 v[118:121], v0, s[22:23]
	s_add_u32 s22, s18, 0x900000
	s_addc_u32 s23, s19, 0
	global_load_dwordx4 v[122:125], v0, s[22:23]
	s_add_u32 s22, s18, 0xa00000
	s_addc_u32 s23, s19, 0
	global_load_dwordx4 v[126:129], v0, s[22:23]
	global_load_dwordx4 v[130:133], v0, s[20:21] offset:1024
	global_load_dwordx4 v[134:137], v0, s[18:19] offset:1024
	s_add_u32 s22, s18, 0x100000
	s_addc_u32 s23, s19, 0
	global_load_dwordx4 v[138:141], v0, s[22:23] offset:1024
	s_add_u32 s22, s18, 0x200000
	s_addc_u32 s23, s19, 0
	global_load_dwordx4 v[142:145], v0, s[22:23] offset:1024
	s_add_u32 s22, s18, 0x300000
	s_addc_u32 s23, s19, 0
	global_load_dwordx4 v[146:149], v0, s[22:23] offset:1024
	s_add_u32 s22, s18, 0x400000
	s_addc_u32 s23, s19, 0
	global_load_dwordx4 v[150:153], v0, s[22:23] offset:1024
	s_add_u32 s22, s18, 0x500000
	s_addc_u32 s23, s19, 0
	global_load_dwordx4 v[154:157], v0, s[22:23] offset:1024
	s_add_u32 s22, s18, 0x600000
	s_addc_u32 s23, s19, 0
	global_load_dwordx4 v[158:161], v0, s[22:23] offset:1024
	s_add_u32 s22, s18, 0x700000
	s_addc_u32 s23, s19, 0
	global_load_dwordx4 v[162:165], v0, s[22:23] offset:1024
	s_add_u32 s22, s18, 0x800000
	s_addc_u32 s23, s19, 0
	global_load_dwordx4 v[166:169], v0, s[22:23] offset:1024
	s_add_u32 s22, s18, 0x900000
	s_addc_u32 s23, s19, 0
	global_load_dwordx4 v[170:173], v0, s[22:23] offset:1024
	s_add_u32 s22, s18, 0xa00000
	s_addc_u32 s23, s19, 0
	global_load_dwordx4 v[174:177], v0, s[22:23] offset:1024
	global_load_dwordx4 v[178:181], v0, s[20:21] offset:2048
	global_load_dwordx4 v[182:185], v0, s[18:19] offset:2048
	s_add_u32 s22, s18, 0x100000
	s_addc_u32 s23, s19, 0
	global_load_dwordx4 v[186:189], v0, s[22:23] offset:2048
	s_add_u32 s22, s18, 0x200000
	s_addc_u32 s23, s19, 0
	global_load_dwordx4 v[190:193], v0, s[22:23] offset:2048
	s_add_u32 s22, s18, 0x300000
	s_addc_u32 s23, s19, 0
	global_load_dwordx4 v[194:197], v0, s[22:23] offset:2048
	s_add_u32 s22, s18, 0x400000
	s_addc_u32 s23, s19, 0
	global_load_dwordx4 v[198:201], v0, s[22:23] offset:2048
	s_add_u32 s22, s18, 0x500000
	s_addc_u32 s23, s19, 0
	global_load_dwordx4 v[202:205], v0, s[22:23] offset:2048
	s_add_u32 s22, s18, 0x600000
	s_addc_u32 s23, s19, 0
	global_load_dwordx4 v[206:209], v0, s[22:23] offset:2048
	s_add_u32 s22, s18, 0x700000
	s_addc_u32 s23, s19, 0
	global_load_dwordx4 v[210:213], v0, s[22:23] offset:2048
	s_add_u32 s22, s18, 0x800000
	s_addc_u32 s23, s19, 0
	global_load_dwordx4 v[214:217], v0, s[22:23] offset:2048
	s_add_u32 s22, s18, 0x900000
	s_addc_u32 s23, s19, 0
	global_load_dwordx4 v[218:221], v0, s[22:23] offset:2048
	s_add_u32 s22, s18, 0xa00000
	s_addc_u32 s23, s19, 0
	global_load_dwordx4 v[222:225], v0, s[22:23] offset:2048
	s_waitcnt vmcnt(24)
	v_pk_add_f32 v[50:51], v[82:83], v[86:87]
	v_pk_add_f32 v[52:53], v[84:85], v[88:89]
	v_pk_add_f32 v[50:51], v[50:51], v[90:91]
	v_pk_add_f32 v[52:53], v[52:53], v[92:93]
	v_pk_add_f32 v[50:51], v[50:51], v[94:95]
	v_pk_add_f32 v[52:53], v[52:53], v[96:97]
	v_pk_add_f32 v[50:51], v[50:51], v[98:99]
	v_pk_add_f32 v[52:53], v[52:53], v[100:101]
	v_pk_add_f32 v[50:51], v[50:51], v[102:103]
	v_pk_add_f32 v[52:53], v[52:53], v[104:105]
	v_pk_add_f32 v[50:51], v[50:51], v[106:107]
	v_pk_add_f32 v[52:53], v[52:53], v[108:109]
	v_pk_add_f32 v[50:51], v[50:51], v[110:111]
	v_pk_add_f32 v[52:53], v[52:53], v[112:113]
	v_pk_add_f32 v[50:51], v[50:51], v[114:115]
	v_pk_add_f32 v[52:53], v[52:53], v[116:117]
	v_pk_add_f32 v[50:51], v[50:51], v[118:119]
	v_pk_add_f32 v[52:53], v[52:53], v[120:121]
	v_pk_add_f32 v[50:51], v[50:51], v[122:123]
	v_pk_add_f32 v[52:53], v[52:53], v[124:125]
	v_pk_add_f32 v[50:51], v[50:51], v[126:127]
	v_pk_add_f32 v[52:53], v[52:53], v[128:129]
	global_store_dwordx4 v0, v[50:53], s[20:21]
	global_load_dwordx4 v[82:85], v0, s[20:21] offset:3072
	global_load_dwordx4 v[86:89], v0, s[18:19] offset:3072
	s_add_u32 s22, s18, 0x100000
	s_addc_u32 s23, s19, 0
	global_load_dwordx4 v[90:93], v0, s[22:23] offset:3072
	s_add_u32 s22, s18, 0x200000
	s_addc_u32 s23, s19, 0
	global_load_dwordx4 v[94:97], v0, s[22:23] offset:3072
	s_add_u32 s22, s18, 0x300000
	s_addc_u32 s23, s19, 0
	global_load_dwordx4 v[98:101], v0, s[22:23] offset:3072
	s_add_u32 s22, s18, 0x400000
	s_addc_u32 s23, s19, 0
	global_load_dwordx4 v[102:105], v0, s[22:23] offset:3072
	s_add_u32 s22, s18, 0x500000
	s_addc_u32 s23, s19, 0
	global_load_dwordx4 v[106:109], v0, s[22:23] offset:3072
	s_add_u32 s22, s18, 0x600000
	s_addc_u32 s23, s19, 0
	global_load_dwordx4 v[110:113], v0, s[22:23] offset:3072
	s_add_u32 s22, s18, 0x700000
	s_addc_u32 s23, s19, 0
	global_load_dwordx4 v[114:117], v0, s[22:23] offset:3072
	s_add_u32 s22, s18, 0x800000
	s_addc_u32 s23, s19, 0
	global_load_dwordx4 v[118:121], v0, s[22:23] offset:3072
	s_add_u32 s22, s18, 0x900000
	s_addc_u32 s23, s19, 0
	global_load_dwordx4 v[122:125], v0, s[22:23] offset:3072
	s_add_u32 s22, s18, 0xa00000
	s_addc_u32 s23, s19, 0
	global_load_dwordx4 v[126:129], v0, s[22:23] offset:3072
	s_waitcnt vmcnt(25)
; __device__ __forceinline__ void sample_assemble(const float* base, const float* XSP, int nsp, int s, float* xr, int lane) {
;     const f32x4* br = (const f32x4*)base + lane; f32x4* o = (f32x4*)xr + lane;
; #pragma unroll
;     for (int j = 0; j < 8; ++j) { f32x4 v = br[64 * j];
;         for (int sp = 0; sp < nsp; ++sp) v += *((const f32x4*)(XSP + ((size_t)sp * NS + s) * DM) + lane + 64 * j);
;         o[64 * j] = v; }
; }
; __global__ void __launch_bounds__(NTHR, 2) fwd_kernel(Args a) {
;     ...
;     for (int m = gw; m < MREAL; m += NGW) {
;         if (m >= MP) { sample_assemble(XR + (size_t)m * DM, XSP, 11, m - MP, XR + (size_t)m * DM, lane); rms_row_f32(XR + (size_t)m * DM, final_norm_g, out + O_YS + (size_t)(m - MP) * DM, lane); }
	v_pk_add_f32 v[54:55], v[130:131], v[134:135]
	v_pk_add_f32 v[56:57], v[132:133], v[136:137]
	v_pk_add_f32 v[54:55], v[54:55], v[138:139]
	v_pk_add_f32 v[56:57], v[56:57], v[140:141]
	v_pk_add_f32 v[54:55], v[54:55], v[142:143]
	v_pk_add_f32 v[56:57], v[56:57], v[144:145]
	v_pk_add_f32 v[54:55], v[54:55], v[146:147]
	v_pk_add_f32 v[56:57], v[56:57], v[148:149]
	v_pk_add_f32 v[54:55], v[54:55], v[150:151]
	v_pk_add_f32 v[56:57], v[56:57], v[152:153]
	v_pk_add_f32 v[54:55], v[54:55], v[154:155]
	v_pk_add_f32 v[56:57], v[56:57], v[156:157]
	v_pk_add_f32 v[54:55], v[54:55], v[158:159]
	v_pk_add_f32 v[56:57], v[56:57], v[160:161]
	v_pk_add_f32 v[54:55], v[54:55], v[162:163]
	v_pk_add_f32 v[56:57], v[56:57], v[164:165]
	v_pk_add_f32 v[54:55], v[54:55], v[166:167]
	v_pk_add_f32 v[56:57], v[56:57], v[168:169]
	v_pk_add_f32 v[54:55], v[54:55], v[170:171]
	v_pk_add_f32 v[56:57], v[56:57], v[172:173]
	v_pk_add_f32 v[54:55], v[54:55], v[174:175]
	v_pk_add_f32 v[56:57], v[56:57], v[176:177]
	global_store_dwordx4 v0, v[54:57], s[20:21] offset:1024
	global_load_dwordx4 v[130:133], v48, s[20:21]
	global_load_dwordx4 v[134:137], v48, s[18:19]
	s_add_u32 s22, s18, 0x100000
	s_addc_u32 s23, s19, 0
	global_load_dwordx4 v[138:141], v48, s[22:23]
	s_add_u32 s22, s18, 0x200000
	s_addc_u32 s23, s19, 0
	global_load_dwordx4 v[142:145], v48, s[22:23]
	s_add_u32 s22, s18, 0x300000
	s_addc_u32 s23, s19, 0
	global_load_dwordx4 v[146:149], v48, s[22:23]
	s_add_u32 s22, s18, 0x400000
	s_addc_u32 s23, s19, 0
	global_load_dwordx4 v[150:153], v48, s[22:23]
	s_add_u32 s22, s18, 0x500000
	s_addc_u32 s23, s19, 0
	global_load_dwordx4 v[154:157], v48, s[22:23]
	s_add_u32 s22, s18, 0x600000
	s_addc_u32 s23, s19, 0
	global_load_dwordx4 v[158:161], v48, s[22:23]
	s_add_u32 s22, s18, 0x700000
	s_addc_u32 s23, s19, 0
	global_load_dwordx4 v[162:165], v48, s[22:23]
	s_add_u32 s22, s18, 0x800000
	s_addc_u32 s23, s19, 0
	global_load_dwordx4 v[166:169], v48, s[22:23]
	s_add_u32 s22, s18, 0x900000
	s_addc_u32 s23, s19, 0
	global_load_dwordx4 v[170:173], v48, s[22:23]
	s_add_u32 s22, s18, 0xa00000
	s_addc_u32 s23, s19, 0
	global_load_dwordx4 v[174:177], v48, s[22:23]
	s_waitcnt vmcnt(26)
	v_pk_add_f32 v[58:59], v[178:179], v[182:183]
	v_pk_add_f32 v[60:61], v[180:181], v[184:185]
	v_pk_add_f32 v[58:59], v[58:59], v[186:187]
	v_pk_add_f32 v[60:61], v[60:61], v[188:189]
	v_pk_add_f32 v[58:59], v[58:59], v[190:191]
	v_pk_add_f32 v[60:61], v[60:61], v[192:193]
	v_pk_add_f32 v[58:59], v[58:59], v[194:195]
	v_pk_add_f32 v[60:61], v[60:61], v[196:197]
	v_pk_add_f32 v[58:59], v[58:59], v[198:199]
	v_pk_add_f32 v[60:61], v[60:61], v[200:201]
	v_pk_add_f32 v[58:59], v[58:59], v[202:203]
	v_pk_add_f32 v[60:61], v[60:61], v[204:205]
	v_pk_add_f32 v[58:59], v[58:59], v[206:207]
	v_pk_add_f32 v[60:61], v[60:61], v[208:209]
	v_pk_add_f32 v[58:59], v[58:59], v[210:211]
	v_pk_add_f32 v[60:61], v[60:61], v[212:213]
	v_pk_add_f32 v[58:59], v[58:59], v[214:215]
	v_pk_add_f32 v[60:61], v[60:61], v[216:217]
	v_pk_add_f32 v[58:59], v[58:59], v[218:219]
	v_pk_add_f32 v[60:61], v[60:61], v[220:221]
	v_pk_add_f32 v[58:59], v[58:59], v[222:223]
	v_pk_add_f32 v[60:61], v[60:61], v[224:225]
	global_store_dwordx4 v0, v[58:61], s[20:21] offset:2048
	global_load_dwordx4 v[178:181], v48, s[20:21] offset:1024
	global_load_dwordx4 v[182:185], v48, s[18:19] offset:1024
	s_add_u32 s22, s18, 0x100000
	s_addc_u32 s23, s19, 0
	global_load_dwordx4 v[186:189], v48, s[22:23] offset:1024
	s_add_u32 s22, s18, 0x200000
	s_addc_u32 s23, s19, 0
	global_load_dwordx4 v[190:193], v48, s[22:23] offset:1024
	s_add_u32 s22, s18, 0x300000
	s_addc_u32 s23, s19, 0
	global_load_dwordx4 v[194:197], v48, s[22:23] offset:1024
	s_add_u32 s22, s18, 0x400000
	s_addc_u32 s23, s19, 0
	global_load_dwordx4 v[198:201], v48, s[22:23] offset:1024
	s_add_u32 s22, s18, 0x500000
	s_addc_u32 s23, s19, 0
	global_load_dwordx4 v[202:205], v48, s[22:23] offset:1024
	s_add_u32 s22, s18, 0x600000
	s_addc_u32 s23, s19, 0
	global_load_dwordx4 v[206:209], v48, s[22:23] offset:1024
	s_add_u32 s22, s18, 0x700000
	s_addc_u32 s23, s19, 0
	global_load_dwordx4 v[210:213], v48, s[22:23] offset:1024
	s_add_u32 s22, s18, 0x800000
	s_addc_u32 s23, s19, 0
	global_load_dwordx4 v[214:217], v48, s[22:23] offset:1024
	s_add_u32 s22, s18, 0x900000
	s_addc_u32 s23, s19, 0
	global_load_dwordx4 v[218:221], v48, s[22:23] offset:1024
	s_add_u32 s22, s18, 0xa00000
	s_addc_u32 s23, s19, 0
	global_load_dwordx4 v[222:225], v48, s[22:23] offset:1024
	s_waitcnt vmcnt(26)
; __device__ __forceinline__ void sample_assemble(const float* base, const float* XSP, int nsp, int s, float* xr, int lane) {
;     const f32x4* br = (const f32x4*)base + lane; f32x4* o = (f32x4*)xr + lane;
; #pragma unroll
;     for (int j = 0; j < 8; ++j) { f32x4 v = br[64 * j];
;         for (int sp = 0; sp < nsp; ++sp) v += *((const f32x4*)(XSP + ((size_t)sp * NS + s) * DM) + lane + 64 * j);
;         o[64 * j] = v; }
; }
; __global__ void __launch_bounds__(NTHR, 2) fwd_kernel(Args a) {
;     ...
;     for (int m = gw; m < MREAL; m += NGW) {
;         if (m >= MP) { sample_assemble(XR + (size_t)m * DM, XSP, 11, m - MP, XR + (size_t)m * DM, lane); rms_row_f32(XR + (size_t)m * DM, final_norm_g, out + O_YS + (size_t)(m - MP) * DM, lane); }
	v_pk_add_f32 v[62:63], v[82:83], v[86:87]
	v_pk_add_f32 v[64:65], v[84:85], v[88:89]
	v_pk_add_f32 v[62:63], v[62:63], v[90:91]
	v_pk_add_f32 v[64:65], v[64:65], v[92:93]
	v_pk_add_f32 v[62:63], v[62:63], v[94:95]
	v_pk_add_f32 v[64:65], v[64:65], v[96:97]
	v_pk_add_f32 v[62:63], v[62:63], v[98:99]
	v_pk_add_f32 v[64:65], v[64:65], v[100:101]
	v_pk_add_f32 v[62:63], v[62:63], v[102:103]
	v_pk_add_f32 v[64:65], v[64:65], v[104:105]
	v_pk_add_f32 v[62:63], v[62:63], v[106:107]
	v_pk_add_f32 v[64:65], v[64:65], v[108:109]
	v_pk_add_f32 v[62:63], v[62:63], v[110:111]
	v_pk_add_f32 v[64:65], v[64:65], v[112:113]
	v_pk_add_f32 v[62:63], v[62:63], v[114:115]
	v_pk_add_f32 v[64:65], v[64:65], v[116:117]
	v_pk_add_f32 v[62:63], v[62:63], v[118:119]
	v_pk_add_f32 v[64:65], v[64:65], v[120:121]
	v_pk_add_f32 v[62:63], v[62:63], v[122:123]
	v_pk_add_f32 v[64:65], v[64:65], v[124:125]
	v_pk_add_f32 v[62:63], v[62:63], v[126:127]
	v_pk_add_f32 v[64:65], v[64:65], v[128:129]
	global_store_dwordx4 v0, v[62:65], s[20:21] offset:3072
	global_load_dwordx4 v[82:85], v48, s[20:21] offset:2048
	global_load_dwordx4 v[86:89], v48, s[18:19] offset:2048
	s_add_u32 s22, s18, 0x100000
	s_addc_u32 s23, s19, 0
	global_load_dwordx4 v[90:93], v48, s[22:23] offset:2048
	s_add_u32 s22, s18, 0x200000
	s_addc_u32 s23, s19, 0
	global_load_dwordx4 v[94:97], v48, s[22:23] offset:2048
	s_add_u32 s22, s18, 0x300000
	s_addc_u32 s23, s19, 0
	global_load_dwordx4 v[98:101], v48, s[22:23] offset:2048
	s_add_u32 s22, s18, 0x400000
	s_addc_u32 s23, s19, 0
	global_load_dwordx4 v[102:105], v48, s[22:23] offset:2048
	s_add_u32 s22, s18, 0x500000
	s_addc_u32 s23, s19, 0
	global_load_dwordx4 v[106:109], v48, s[22:23] offset:2048
	s_add_u32 s22, s18, 0x600000
	s_addc_u32 s23, s19, 0
	global_load_dwordx4 v[110:113], v48, s[22:23] offset:2048
	s_add_u32 s22, s18, 0x700000
	s_addc_u32 s23, s19, 0
	global_load_dwordx4 v[114:117], v48, s[22:23] offset:2048
	s_add_u32 s22, s18, 0x800000
	s_addc_u32 s23, s19, 0
	global_load_dwordx4 v[118:121], v48, s[22:23] offset:2048
	s_add_u32 s22, s18, 0x900000
	s_addc_u32 s23, s19, 0
	global_load_dwordx4 v[122:125], v48, s[22:23] offset:2048
	s_add_u32 s22, s18, 0xa00000
	s_addc_u32 s23, s19, 0
	global_load_dwordx4 v[126:129], v48, s[22:23] offset:2048
	s_waitcnt vmcnt(26)
	v_pk_add_f32 v[66:67], v[130:131], v[134:135]
	v_pk_add_f32 v[68:69], v[132:133], v[136:137]
	v_pk_add_f32 v[66:67], v[66:67], v[138:139]
	v_pk_add_f32 v[68:69], v[68:69], v[140:141]
	v_pk_add_f32 v[66:67], v[66:67], v[142:143]
	v_pk_add_f32 v[68:69], v[68:69], v[144:145]
	v_pk_add_f32 v[66:67], v[66:67], v[146:147]
	v_pk_add_f32 v[68:69], v[68:69], v[148:149]
	v_pk_add_f32 v[66:67], v[66:67], v[150:151]
	v_pk_add_f32 v[68:69], v[68:69], v[152:153]
	v_pk_add_f32 v[66:67], v[66:67], v[154:155]
	v_pk_add_f32 v[68:69], v[68:69], v[156:157]
	v_pk_add_f32 v[66:67], v[66:67], v[158:159]
	v_pk_add_f32 v[68:69], v[68:69], v[160:161]
	v_pk_add_f32 v[66:67], v[66:67], v[162:163]
	v_pk_add_f32 v[68:69], v[68:69], v[164:165]
	v_pk_add_f32 v[66:67], v[66:67], v[166:167]
	v_pk_add_f32 v[68:69], v[68:69], v[168:169]
	v_pk_add_f32 v[66:67], v[66:67], v[170:171]
	v_pk_add_f32 v[68:69], v[68:69], v[172:173]
	v_pk_add_f32 v[66:67], v[66:67], v[174:175]
	v_pk_add_f32 v[68:69], v[68:69], v[176:177]
	global_store_dwordx4 v48, v[66:69], s[20:21]
	global_load_dwordx4 v[130:133], v48, s[20:21] offset:3072
	global_load_dwordx4 v[134:137], v48, s[18:19] offset:3072
	s_add_u32 s22, s18, 0x100000
	s_addc_u32 s23, s19, 0
	global_load_dwordx4 v[138:141], v48, s[22:23] offset:3072
	s_add_u32 s22, s18, 0x200000
	s_addc_u32 s23, s19, 0
	global_load_dwordx4 v[142:145], v48, s[22:23] offset:3072
	s_add_u32 s22, s18, 0x300000
	s_addc_u32 s23, s19, 0
	global_load_dwordx4 v[146:149], v48, s[22:23] offset:3072
	s_add_u32 s22, s18, 0x400000
	s_addc_u32 s23, s19, 0
	global_load_dwordx4 v[150:153], v48, s[22:23] offset:3072
	s_add_u32 s22, s18, 0x500000
	s_addc_u32 s23, s19, 0
	global_load_dwordx4 v[154:157], v48, s[22:23] offset:3072
	s_add_u32 s22, s18, 0x600000
	s_addc_u32 s23, s19, 0
	global_load_dwordx4 v[158:161], v48, s[22:23] offset:3072
	s_add_u32 s22, s18, 0x700000
	s_addc_u32 s23, s19, 0
	global_load_dwordx4 v[162:165], v48, s[22:23] offset:3072
	s_add_u32 s22, s18, 0x800000
	s_addc_u32 s23, s19, 0
	global_load_dwordx4 v[166:169], v48, s[22:23] offset:3072
	s_add_u32 s22, s18, 0x900000
	s_addc_u32 s23, s19, 0
	global_load_dwordx4 v[170:173], v48, s[22:23] offset:3072
	s_add_u32 s22, s18, 0xa00000
	s_addc_u32 s23, s19, 0
	global_load_dwordx4 v[174:177], v48, s[22:23] offset:3072
	s_waitcnt vmcnt(26)
	v_pk_add_f32 v[70:71], v[178:179], v[182:183]
	v_pk_add_f32 v[72:73], v[180:181], v[184:185]
	v_pk_add_f32 v[70:71], v[70:71], v[186:187]
	v_pk_add_f32 v[72:73], v[72:73], v[188:189]
	v_pk_add_f32 v[70:71], v[70:71], v[190:191]
	v_pk_add_f32 v[72:73], v[72:73], v[192:193]
	v_pk_add_f32 v[70:71], v[70:71], v[194:195]
	v_pk_add_f32 v[72:73], v[72:73], v[196:197]
	v_pk_add_f32 v[70:71], v[70:71], v[198:199]
	v_pk_add_f32 v[72:73], v[72:73], v[200:201]
	v_pk_add_f32 v[70:71], v[70:71], v[202:203]
	v_pk_add_f32 v[72:73], v[72:73], v[204:205]
	v_pk_add_f32 v[70:71], v[70:71], v[206:207]
	v_pk_add_f32 v[72:73], v[72:73], v[208:209]
	v_pk_add_f32 v[70:71], v[70:71], v[210:211]
	v_pk_add_f32 v[72:73], v[72:73], v[212:213]
	v_pk_add_f32 v[70:71], v[70:71], v[214:215]
	v_pk_add_f32 v[72:73], v[72:73], v[216:217]
	v_pk_add_f32 v[70:71], v[70:71], v[218:219]
	v_pk_add_f32 v[72:73], v[72:73], v[220:221]
	v_pk_add_f32 v[70:71], v[70:71], v[222:223]
	v_pk_add_f32 v[72:73], v[72:73], v[224:225]
	global_store_dwordx4 v48, v[70:73], s[20:21] offset:1024
	s_waitcnt vmcnt(14)
; __device__ __forceinline__ void rms_row_f32(const float* xrow, const float* g, float* orow, int lane) {
;     const f32x4* xr = (const f32x4*)xrow + lane; f32x4 v[8]; float s = 0.f;
; #pragma unroll
;     for (int j = 0; j < 8; ++j) { v[j] = xr[64 * j]; s += (v[j].x * v[j].x + v[j].y * v[j].y) + (v[j].z * v[j].z + v[j].w * v[j].w); }
;     const float rstd = rsqrtf(wave_sum(s) * (1.f / DM) + EPS);
;     const f32x4* gr = (const f32x4*)g + lane; f32x4* o = (f32x4*)orow + lane;
; #pragma unroll
;     for (int j = 0; j < 8; ++j) { const f32x4 gg = gr[64 * j]; o[64 * j] = v[j] * rstd * gg; }
; }
; __device__ __forceinline__ void sample_assemble(const float* base, const float* XSP, int nsp, int s, float* xr, int lane) {
;     const f32x4* br = (const f32x4*)base + lane; f32x4* o = (f32x4*)xr + lane;
; #pragma unroll
;     for (int j = 0; j < 8; ++j) { f32x4 v = br[64 * j];
;         for (int sp = 0; sp < nsp; ++sp) v += *((const f32x4*)(XSP + ((size_t)sp * NS + s) * DM) + lane + 64 * j);
;         o[64 * j] = v; }
; }
	v_pk_add_f32 v[74:75], v[82:83], v[86:87]
	v_pk_add_f32 v[76:77], v[84:85], v[88:89]
	v_pk_add_f32 v[74:75], v[74:75], v[90:91]
	v_pk_add_f32 v[76:77], v[76:77], v[92:93]
	v_pk_add_f32 v[74:75], v[74:75], v[94:95]
	v_pk_add_f32 v[76:77], v[76:77], v[96:97]
	v_pk_add_f32 v[74:75], v[74:75], v[98:99]
	v_pk_add_f32 v[76:77], v[76:77], v[100:101]
	v_pk_add_f32 v[74:75], v[74:75], v[102:103]
	v_pk_add_f32 v[76:77], v[76:77], v[104:105]
	v_pk_add_f32 v[74:75], v[74:75], v[106:107]
	v_pk_add_f32 v[76:77], v[76:77], v[108:109]
	v_pk_add_f32 v[74:75], v[74:75], v[110:111]
	v_pk_add_f32 v[76:77], v[76:77], v[112:113]
	v_pk_add_f32 v[74:75], v[74:75], v[114:115]
	v_pk_add_f32 v[76:77], v[76:77], v[116:117]
	v_pk_add_f32 v[74:75], v[74:75], v[118:119]
	v_pk_add_f32 v[76:77], v[76:77], v[120:121]
	v_pk_add_f32 v[74:75], v[74:75], v[122:123]
	v_pk_add_f32 v[76:77], v[76:77], v[124:125]
	v_pk_add_f32 v[74:75], v[74:75], v[126:127]
	v_pk_add_f32 v[76:77], v[76:77], v[128:129]
	global_store_dwordx4 v48, v[74:77], s[20:21] offset:2048
	s_waitcnt vmcnt(2)
	v_pk_add_f32 v[78:79], v[130:131], v[134:135]
	v_pk_add_f32 v[80:81], v[132:133], v[136:137]
	v_pk_add_f32 v[78:79], v[78:79], v[138:139]
	v_pk_add_f32 v[80:81], v[80:81], v[140:141]
	v_pk_add_f32 v[78:79], v[78:79], v[142:143]
	v_pk_add_f32 v[80:81], v[80:81], v[144:145]
	v_pk_add_f32 v[78:79], v[78:79], v[146:147]
	v_pk_add_f32 v[80:81], v[80:81], v[148:149]
	v_pk_add_f32 v[78:79], v[78:79], v[150:151]
	v_pk_add_f32 v[80:81], v[80:81], v[152:153]
	v_pk_add_f32 v[78:79], v[78:79], v[154:155]
	v_pk_add_f32 v[80:81], v[80:81], v[156:157]
	v_pk_add_f32 v[78:79], v[78:79], v[158:159]
	v_pk_add_f32 v[80:81], v[80:81], v[160:161]
	v_pk_add_f32 v[78:79], v[78:79], v[162:163]
	v_pk_add_f32 v[80:81], v[80:81], v[164:165]
	v_pk_add_f32 v[78:79], v[78:79], v[166:167]
	v_pk_add_f32 v[80:81], v[80:81], v[168:169]
	v_pk_add_f32 v[78:79], v[78:79], v[170:171]
	v_pk_add_f32 v[80:81], v[80:81], v[172:173]
	v_pk_add_f32 v[78:79], v[78:79], v[174:175]
	v_pk_add_f32 v[80:81], v[80:81], v[176:177]
	global_store_dwordx4 v48, v[78:81], s[20:21] offset:3072
	v_mul_f32_e32 v226, v51, v51
	v_mul_f32_e32 v228, v53, v53
	v_fmac_f32_e32 v226, v50, v50
	v_fmac_f32_e32 v228, v52, v52
	v_add_f32_e32 v226, v226, v228
	v_mul_f32_e32 v49, v55, v55
	v_mul_f32_e32 v228, v57, v57
	v_fmac_f32_e32 v49, v54, v54
	v_fmac_f32_e32 v228, v56, v56
	v_add_f32_e32 v49, v49, v228
	v_add_f32_e32 v226, v226, v49
	v_mul_f32_e32 v49, v59, v59
	v_mul_f32_e32 v228, v61, v61
	v_fmac_f32_e32 v49, v58, v58
	v_fmac_f32_e32 v228, v60, v60
	v_add_f32_e32 v49, v49, v228
	v_add_f32_e32 v226, v226, v49
	v_mul_f32_e32 v49, v63, v63
	v_mul_f32_e32 v228, v65, v65
	v_fmac_f32_e32 v49, v62, v62
	v_fmac_f32_e32 v228, v64, v64
	v_add_f32_e32 v49, v49, v228
	v_add_f32_e32 v226, v226, v49
	v_mul_f32_e32 v49, v67, v67
	v_mul_f32_e32 v228, v69, v69
	v_fmac_f32_e32 v49, v66, v66
	v_fmac_f32_e32 v228, v68, v68
	v_add_f32_e32 v49, v49, v228
	v_add_f32_e32 v226, v226, v49
	v_mul_f32_e32 v49, v71, v71
	v_mul_f32_e32 v228, v73, v73
	v_fmac_f32_e32 v49, v70, v70
	v_fmac_f32_e32 v228, v72, v72
	v_add_f32_e32 v49, v49, v228
	v_add_f32_e32 v226, v226, v49
	v_mul_f32_e32 v49, v75, v75
	v_mul_f32_e32 v228, v77, v77
	v_fmac_f32_e32 v49, v74, v74
	v_fmac_f32_e32 v228, v76, v76
	v_add_f32_e32 v49, v49, v228
	v_add_f32_e32 v226, v226, v49
	v_mul_f32_e32 v49, v79, v79
	v_mul_f32_e32 v228, v81, v81
	v_fmac_f32_e32 v49, v78, v78
	v_fmac_f32_e32 v228, v80, v80
	v_add_f32_e32 v49, v49, v228
	v_add_f32_e32 v226, v226, v49
	ds_bpermute_b32 v229, v3, v226
	s_waitcnt lgkmcnt(0)
	v_add_f32_e32 v226, v226, v229
	ds_bpermute_b32 v229, v4, v226
	s_waitcnt lgkmcnt(0)
	v_add_f32_e32 v226, v226, v229
	ds_bpermute_b32 v229, v5, v226
	s_waitcnt lgkmcnt(0)
	v_add_f32_e32 v226, v226, v229
	ds_bpermute_b32 v229, v6, v226
	s_waitcnt lgkmcnt(0)
	v_add_f32_e32 v226, v226, v229
	ds_bpermute_b32 v229, v7, v226
	s_waitcnt lgkmcnt(0)
	v_add_f32_e32 v226, v226, v229
	ds_bpermute_b32 v229, v8, v226
	s_waitcnt lgkmcnt(0)
	v_add_f32_e32 v226, v226, v229
	v_fmamk_f32 v226, v226, 0x3a000000, v9
	v_mul_f32_e32 v49, 0x4b800000, v226
	v_cmp_gt_f32_e32 vcc, s12, v226
	s_nop 1
	v_cndmask_b32_e32 v226, v226, v49, vcc
	v_rsq_f32_e32 v226, v226
	s_nop 0
	v_mul_f32_e32 v49, 0x45800000, v226
	v_cndmask_b32_e32 v226, v226, v49, vcc
	s_lshl_b32 s16, s14, 13
	s_add_u32 s16, s16, 0x4000000
	s_add_u32 s16, s6, s16
	s_addc_u32 s17, s7, 0
	v_pk_mul_f32 v[50:51], v[226:227], v[50:51] op_sel_hi:[0,1]
	v_pk_mul_f32 v[52:53], v[226:227], v[52:53] op_sel_hi:[0,1]
	v_pk_mul_f32 v[50:51], v[50:51], v[16:17]
	v_pk_mul_f32 v[52:53], v[52:53], v[18:19]
	global_store_dwordx4 v0, v[50:53], s[16:17]
	v_pk_mul_f32 v[54:55], v[226:227], v[54:55] op_sel_hi:[0,1]
	v_pk_mul_f32 v[56:57], v[226:227], v[56:57] op_sel_hi:[0,1]
	v_pk_mul_f32 v[54:55], v[54:55], v[20:21]
	v_pk_mul_f32 v[56:57], v[56:57], v[22:23]
	global_store_dwordx4 v0, v[54:57], s[16:17] offset:1024
	v_pk_mul_f32 v[58:59], v[226:227], v[58:59] op_sel_hi:[0,1]
	v_pk_mul_f32 v[60:61], v[226:227], v[60:61] op_sel_hi:[0,1]
	v_pk_mul_f32 v[58:59], v[58:59], v[24:25]
	v_pk_mul_f32 v[60:61], v[60:61], v[26:27]
	global_store_dwordx4 v0, v[58:61], s[16:17] offset:2048
	v_pk_mul_f32 v[62:63], v[226:227], v[62:63] op_sel_hi:[0,1]
	v_pk_mul_f32 v[64:65], v[226:227], v[64:65] op_sel_hi:[0,1]
	v_pk_mul_f32 v[62:63], v[62:63], v[28:29]
	v_pk_mul_f32 v[64:65], v[64:65], v[30:31]
	global_store_dwordx4 v0, v[62:65], s[16:17] offset:3072
	v_pk_mul_f32 v[66:67], v[226:227], v[66:67] op_sel_hi:[0,1]
	v_pk_mul_f32 v[68:69], v[226:227], v[68:69] op_sel_hi:[0,1]
	v_pk_mul_f32 v[66:67], v[66:67], v[32:33]
	v_pk_mul_f32 v[68:69], v[68:69], v[34:35]
	global_store_dwordx4 v2, v[66:69], s[16:17]
	v_pk_mul_f32 v[70:71], v[226:227], v[70:71] op_sel_hi:[0,1]
	v_pk_mul_f32 v[72:73], v[226:227], v[72:73] op_sel_hi:[0,1]
	v_pk_mul_f32 v[70:71], v[70:71], v[36:37]
	v_pk_mul_f32 v[72:73], v[72:73], v[38:39]
	global_store_dwordx4 v2, v[70:73], s[16:17] offset:1024
	v_pk_mul_f32 v[74:75], v[226:227], v[74:75] op_sel_hi:[0,1]
	v_pk_mul_f32 v[76:77], v[226:227], v[76:77] op_sel_hi:[0,1]
	v_pk_mul_f32 v[74:75], v[74:75], v[40:41]
	v_pk_mul_f32 v[76:77], v[76:77], v[42:43]
	global_store_dwordx4 v2, v[74:77], s[16:17] offset:2048
	v_pk_mul_f32 v[78:79], v[226:227], v[78:79] op_sel_hi:[0,1]
	v_pk_mul_f32 v[80:81], v[226:227], v[80:81] op_sel_hi:[0,1]
	v_pk_mul_f32 v[78:79], v[78:79], v[44:45]
	v_pk_mul_f32 v[80:81], v[80:81], v[46:47]
	global_store_dwordx4 v2, v[78:81], s[16:17] offset:3072
	s_add_i32 s14, s14, s96
	s_cmp_lt_u32 s14, 0x80
	s_cbranch_scc1 .Lfin_sample_loop

; __global__ void __launch_bounds__(NTHR, 2) fwd_kernel(Args a) {
	.amdhsa_kernel _Z10fwd_kernel4Args
		.amdhsa_group_segment_fixed_size 0
		.amdhsa_private_segment_fixed_size 0
		.amdhsa_kernarg_size 416
		.amdhsa_user_sgpr_count 2
		.amdhsa_user_sgpr_dispatch_ptr 0
		.amdhsa_user_sgpr_queue_ptr 0
		.amdhsa_user_sgpr_kernarg_segment_ptr 1
		.amdhsa_user_sgpr_dispatch_id 0
		.amdhsa_user_sgpr_kernarg_preload_length 0
		.amdhsa_user_sgpr_kernarg_preload_offset 0
		.amdhsa_user_sgpr_private_segment_size 0
		.amdhsa_uses_dynamic_stack 0
		.amdhsa_enable_private_segment 0
		.amdhsa_system_sgpr_workgroup_id_x 1
		.amdhsa_system_sgpr_workgroup_id_y 0
		.amdhsa_system_sgpr_workgroup_id_z 0
		.amdhsa_system_sgpr_workgroup_info 0
		.amdhsa_system_vgpr_workitem_id 2
		.amdhsa_next_free_vgpr 256
		.amdhsa_next_free_sgpr 102
		.amdhsa_accum_offset 256
		.amdhsa_reserve_vcc 1
		.amdhsa_float_round_mode_32 0
		.amdhsa_float_round_mode_16_64 0
		.amdhsa_float_denorm_mode_32 3
		.amdhsa_float_denorm_mode_16_64 3
		.amdhsa_dx10_clamp 1
		.amdhsa_ieee_mode 1
		.amdhsa_fp16_overflow 0
		.amdhsa_tg_split 0
		.amdhsa_exception_fp_ieee_invalid_op 0
		.amdhsa_exception_fp_denorm_src 0
		.amdhsa_exception_fp_ieee_div_zero 0
		.amdhsa_exception_fp_ieee_overflow 0
		.amdhsa_exception_fp_ieee_underflow 0
		.amdhsa_exception_fp_ieee_inexact 0
		.amdhsa_exception_int_div_zero 0
	.end_amdhsa_kernel

; __global__ void __launch_bounds__(NTHR, 2) fwd_kernel(Args a) {
amdhsa.kernels:
  - .agpr_count:     0
    .args:
      - .offset:         0
        .size:           160
        .value_kind:     by_value
      - .offset:         160
        .size:           4
        .value_kind:     hidden_block_count_x
      - .offset:         164
        .size:           4
        .value_kind:     hidden_block_count_y
      - .offset:         168
        .size:           4
        .value_kind:     hidden_block_count_z
      - .offset:         172
        .size:           2
        .value_kind:     hidden_group_size_x
      - .offset:         174
        .size:           2
        .value_kind:     hidden_group_size_y
      - .offset:         176
        .size:           2
        .value_kind:     hidden_group_size_z
      - .offset:         178
        .size:           2
        .value_kind:     hidden_remainder_x
      - .offset:         180
        .size:           2
        .value_kind:     hidden_remainder_y
      - .offset:         182
        .size:           2
        .value_kind:     hidden_remainder_z
      - .offset:         200
        .size:           8
        .value_kind:     hidden_global_offset_x
      - .offset:         208
        .size:           8
        .value_kind:     hidden_global_offset_y
      - .offset:         216
        .size:           8
        .value_kind:     hidden_global_offset_z
      - .offset:         224
        .size:           2
        .value_kind:     hidden_grid_dims
      - .offset:         248
        .size:           8
        .value_kind:     hidden_multigrid_sync_arg
      - .offset:         280
        .size:           4
        .value_kind:     hidden_dynamic_lds_size
    .group_segment_fixed_size: 0
    .kernarg_segment_align: 8
    .kernarg_segment_size: 416
    .language:       OpenCL C
    .language_version:
      - 2
      - 0
    .max_flat_workgroup_size: 512
    .name:           _Z10fwd_kernel4Args
    .private_segment_fixed_size: 0
    .sgpr_count:     108
    .sgpr_spill_count: 166
    .symbol:         _Z10fwd_kernel4Args.kd
    .uniform_work_group_size: 1
    .uses_dynamic_stack: false
    .vgpr_count:     256
    .vgpr_spill_count: 0
    .wavefront_size: 64
